# weight-conversion phase: all 32 row loads of an item issued before the LDS writes (was one load in flight per wave)
# speedup vs baseline: 1.0085x; 1.0085x over previous
; #define LAS __attribute__((address_space(3)))
; __device__ __forceinline__ unsigned cvt_pk_bf16(float lo, float hi) { unsigned r; asm volatile("v_cvt_pk_bf16_f32 %0, %1, %2" : "=v"(r) : "v"(lo), "v"(hi)); return r; }
; template <int MAP>
; __device__ __forceinline__ void cvt_item(const float* W, int K, int N, bf16_t* Wt, int ldk, const float* gain, LAS float* scr, int item, int lane) {
;     ...
; #pragma unroll 8
;     for (int i = 0; i < 32; ++i) { const int kk = 2 * i + (lane >> 5); scr[kk * 33 + (lane & 31)] = W[(size_t)(k0 + kk) * N + n0 + (lane & 31)]; }
;     asm volatile("s_waitcnt lgkmcnt(0)" ::: "memory");
;     const int c = lane & 7;
;     float gk[8];
; #pragma unroll
;     for (int j = 0; j < 8; ++j) gk[j] = gain ? gain[k0 + 8 * c + j] : 1.0f;
; #pragma unroll
;     for (int j = 0; j < 4; ++j) { const int n = (lane >> 3) + 8 * j; const LAS float* s = scr + (8 * c) * 33 + n;
;         u32x4 o; o.x = cvt_pk_bf16(s[0 * 33] * gk[0], s[1 * 33] * gk[1]); o.y = cvt_pk_bf16(s[2 * 33] * gk[2], s[3 * 33] * gk[3]);
;         o.z = cvt_pk_bf16(s[4 * 33] * gk[4], s[5 * 33] * gk[5]); o.w = cvt_pk_bf16(s[6 * 33] * gk[6], s[7 * 33] * gk[7]);
;         const int ng = n0 + n; int drow = ng;
;         if (MAP == 1) { const int half = ng / DFF, r = ng % DFF; drow = (r / 128) * 256 + half * 128 + (r % 128); }
;         if (MAP == 2) { drow = ng < 1536 ? ng + 1024 : (ng < 2560 ? ng - 1536 : ng); }
;         *(u32x4*)(Wt + (size_t)drow * ldk + k0 + 8 * c) = o; }
;     asm volatile("s_waitcnt lgkmcnt(0)" ::: "memory");
.LBB0_925:
	v_lshl_add_u64 v[66:67], v[64:65], 0, s[30:31]
	global_load_dword v192, v[66:67], off
	v_lshl_add_u64 v[66:67], v[62:63], 0, s[30:31]
	global_load_dword v193, v[66:67], off
	v_lshl_add_u64 v[66:67], v[60:61], 0, s[30:31]
	global_load_dword v194, v[66:67], off
	v_lshl_add_u64 v[66:67], v[58:59], 0, s[30:31]
	global_load_dword v195, v[66:67], off
	v_lshl_add_u64 v[66:67], v[56:57], 0, s[30:31]
	global_load_dword v196, v[66:67], off
	v_lshl_add_u64 v[66:67], v[54:55], 0, s[30:31]
	global_load_dword v197, v[66:67], off
	v_lshl_add_u64 v[66:67], v[52:53], 0, s[30:31]
	global_load_dword v198, v[66:67], off
	v_lshl_add_u64 v[66:67], v[50:51], 0, s[30:31]
	global_load_dword v199, v[66:67], off
	s_add_u32 s30, s30, 0x2000
	s_addc_u32 s31, s31, 0
	v_lshl_add_u64 v[66:67], v[64:65], 0, s[30:31]
	global_load_dword v200, v[66:67], off
	v_lshl_add_u64 v[66:67], v[62:63], 0, s[30:31]
	global_load_dword v201, v[66:67], off
	v_lshl_add_u64 v[66:67], v[60:61], 0, s[30:31]
	global_load_dword v202, v[66:67], off
	v_lshl_add_u64 v[66:67], v[58:59], 0, s[30:31]
	global_load_dword v203, v[66:67], off
	v_lshl_add_u64 v[66:67], v[56:57], 0, s[30:31]
	global_load_dword v204, v[66:67], off
	v_lshl_add_u64 v[66:67], v[54:55], 0, s[30:31]
	global_load_dword v205, v[66:67], off
	v_lshl_add_u64 v[66:67], v[52:53], 0, s[30:31]
	global_load_dword v206, v[66:67], off
	v_lshl_add_u64 v[66:67], v[50:51], 0, s[30:31]
	global_load_dword v207, v[66:67], off
	s_add_u32 s30, s30, 0x2000
	s_addc_u32 s31, s31, 0
	v_lshl_add_u64 v[66:67], v[64:65], 0, s[30:31]
	global_load_dword v208, v[66:67], off
	v_lshl_add_u64 v[66:67], v[62:63], 0, s[30:31]
	global_load_dword v209, v[66:67], off
	v_lshl_add_u64 v[66:67], v[60:61], 0, s[30:31]
	global_load_dword v210, v[66:67], off
	v_lshl_add_u64 v[66:67], v[58:59], 0, s[30:31]
	global_load_dword v211, v[66:67], off
	v_lshl_add_u64 v[66:67], v[56:57], 0, s[30:31]
	global_load_dword v212, v[66:67], off
	v_lshl_add_u64 v[66:67], v[54:55], 0, s[30:31]
	global_load_dword v213, v[66:67], off
	v_lshl_add_u64 v[66:67], v[52:53], 0, s[30:31]
	global_load_dword v214, v[66:67], off
	v_lshl_add_u64 v[66:67], v[50:51], 0, s[30:31]
	global_load_dword v215, v[66:67], off
	s_add_u32 s30, s30, 0x2000
	s_addc_u32 s31, s31, 0
	v_lshl_add_u64 v[66:67], v[64:65], 0, s[30:31]
	global_load_dword v216, v[66:67], off
	v_lshl_add_u64 v[66:67], v[62:63], 0, s[30:31]
	global_load_dword v217, v[66:67], off
	v_lshl_add_u64 v[66:67], v[60:61], 0, s[30:31]
	global_load_dword v218, v[66:67], off
	v_lshl_add_u64 v[66:67], v[58:59], 0, s[30:31]
	global_load_dword v219, v[66:67], off
	v_lshl_add_u64 v[66:67], v[56:57], 0, s[30:31]
	global_load_dword v220, v[66:67], off
	v_lshl_add_u64 v[66:67], v[54:55], 0, s[30:31]
	global_load_dword v221, v[66:67], off
	v_lshl_add_u64 v[66:67], v[52:53], 0, s[30:31]
	global_load_dword v222, v[66:67], off
	v_lshl_add_u64 v[66:67], v[50:51], 0, s[30:31]
	global_load_dword v223, v[66:67], off
	s_add_u32 s30, s30, 0x2000
	s_addc_u32 s31, s31, 0
	s_waitcnt vmcnt(24)
	ds_write_b32 v41, v192
	ds_write_b32 v41, v193 offset:264
	ds_write_b32 v41, v194 offset:528
	ds_write_b32 v41, v195 offset:792
	ds_write_b32 v41, v196 offset:1056
	ds_write_b32 v41, v197 offset:1320
	ds_write_b32 v41, v198 offset:1584
	ds_write_b32 v41, v199 offset:1848
	v_add_u32_e32 v41, 0x840, v41
	s_waitcnt vmcnt(16)
	ds_write_b32 v41, v200
	ds_write_b32 v41, v201 offset:264
	ds_write_b32 v41, v202 offset:528
	ds_write_b32 v41, v203 offset:792
	ds_write_b32 v41, v204 offset:1056
	ds_write_b32 v41, v205 offset:1320
	ds_write_b32 v41, v206 offset:1584
	ds_write_b32 v41, v207 offset:1848
	v_add_u32_e32 v41, 0x840, v41
	s_waitcnt vmcnt(8)
	ds_write_b32 v41, v208
	ds_write_b32 v41, v209 offset:264
	ds_write_b32 v41, v210 offset:528
	ds_write_b32 v41, v211 offset:792
	ds_write_b32 v41, v212 offset:1056
	ds_write_b32 v41, v213 offset:1320
	ds_write_b32 v41, v214 offset:1584
	ds_write_b32 v41, v215 offset:1848
	v_add_u32_e32 v41, 0x840, v41
	s_waitcnt vmcnt(0)
	ds_write_b32 v41, v216
	ds_write_b32 v41, v217 offset:264
	ds_write_b32 v41, v218 offset:528
	ds_write_b32 v41, v219 offset:792
	ds_write_b32 v41, v220 offset:1056
	ds_write_b32 v41, v221 offset:1320
	ds_write_b32 v41, v222 offset:1584
	ds_write_b32 v41, v223 offset:1848
	v_add_u32_e32 v41, 0x840, v41
	v_add_u32_e32 v45, 0xffffce00, v1
	v_mov_b32_e32 v55, v0
	v_lshrrev_b32_e32 v54, 4, v45
	v_lshlrev_b64 v[54:55], 16, v[54:55]
	v_lshlrev_b32_e32 v56, 15, v39
	v_mov_b32_e32 v57, v0
	v_lshl_add_u64 v[54:55], s[6:7], 0, v[54:55]
	s_waitcnt lgkmcnt(0)
	v_mov_b32_e32 v39, v0
	v_lshl_add_u64 v[54:55], v[54:55], 0, v[56:57]
	ds_read2_b32 v[50:51], v71 offset1:33
	v_mov_b32_e32 v41, v0
	v_lshl_add_u64 v[54:55], v[54:55], 0, v[38:39]
	s_waitcnt lgkmcnt(0)
	v_cvt_pk_bf16_f32 v50, v50, v51
	ds_read2_b32 v[52:53], v71 offset0:66 offset1:99
	v_mov_b32_e32 v43, v0
	v_lshl_add_u64 v[54:55], v[54:55], 0, v[40:41]
	s_waitcnt lgkmcnt(0)
	v_cvt_pk_bf16_f32 v51, v52, v53
	ds_read2_b32 v[52:53], v71 offset0:132 offset1:165
	v_lshl_add_u64 v[56:57], v[54:55], 0, v[42:43]
	s_waitcnt lgkmcnt(0)
	v_cvt_pk_bf16_f32 v52, v52, v53
	ds_read2_b32 v[58:59], v71 offset0:198 offset1:231
	s_waitcnt lgkmcnt(0)
	v_cvt_pk_bf16_f32 v53, v58, v59
	flat_store_dwordx4 v[56:57], v[50:53]
	ds_read2_b32 v[50:51], v71 offset0:8 offset1:41
	v_mov_b32_e32 v45, v0
	s_waitcnt lgkmcnt(0)
	v_cvt_pk_bf16_f32 v50, v50, v51
	ds_read2_b32 v[52:53], v71 offset0:74 offset1:107
	s_waitcnt lgkmcnt(0)
	v_cvt_pk_bf16_f32 v51, v52, v53
	ds_read2_b32 v[52:53], v71 offset0:140 offset1:173
	v_lshl_add_u64 v[58:59], v[54:55], 0, v[44:45]
	s_waitcnt lgkmcnt(0)
	v_cvt_pk_bf16_f32 v52, v52, v53
	ds_read2_b32 v[56:57], v71 offset0:206 offset1:239
	s_waitcnt lgkmcnt(0)
	v_cvt_pk_bf16_f32 v53, v56, v57
	flat_store_dwordx4 v[58:59], v[50:53]
	ds_read2_b32 v[50:51], v71 offset0:16 offset1:49
	v_mov_b32_e32 v47, v0
	s_waitcnt lgkmcnt(0)
	v_cvt_pk_bf16_f32 v50, v50, v51
	ds_read2_b32 v[52:53], v71 offset0:82 offset1:115
	s_waitcnt lgkmcnt(0)
	v_cvt_pk_bf16_f32 v51, v52, v53
	ds_read2_b32 v[52:53], v71 offset0:148 offset1:181
	v_lshl_add_u64 v[58:59], v[54:55], 0, v[46:47]
	s_waitcnt lgkmcnt(0)
	v_cvt_pk_bf16_f32 v52, v52, v53
	ds_read2_b32 v[56:57], v71 offset0:214 offset1:247
	s_waitcnt lgkmcnt(0)
	v_cvt_pk_bf16_f32 v53, v56, v57
	flat_store_dwordx4 v[58:59], v[50:53]
	ds_read2_b32 v[50:51], v71 offset0:24 offset1:57
	v_mov_b32_e32 v49, v0
	s_waitcnt lgkmcnt(0)
	v_cvt_pk_bf16_f32 v50, v50, v51
	ds_read2_b32 v[52:53], v71 offset0:90 offset1:123
	s_waitcnt lgkmcnt(0)
	v_cvt_pk_bf16_f32 v51, v52, v53
	ds_read2_b32 v[52:53], v71 offset0:156 offset1:189
	v_lshl_add_u64 v[54:55], v[54:55], 0, v[48:49]
	s_waitcnt lgkmcnt(0)
	v_cvt_pk_bf16_f32 v52, v52, v53
	ds_read2_b32 v[56:57], v71 offset0:222 offset1:255
	s_waitcnt lgkmcnt(0)
	v_cvt_pk_bf16_f32 v53, v56, v57
	flat_store_dwordx4 v[54:55], v[50:53]
	s_waitcnt lgkmcnt(0)

; #define LAS __attribute__((address_space(3)))
; __device__ __forceinline__ unsigned cvt_pk_bf16(float lo, float hi) { unsigned r; asm volatile("v_cvt_pk_bf16_f32 %0, %1, %2" : "=v"(r) : "v"(lo), "v"(hi)); return r; }
; template <int MAP>
; __device__ __forceinline__ void cvt_item(const float* W, int K, int N, bf16_t* Wt, int ldk, const float* gain, LAS float* scr, int item, int lane) {
;     ...
; #pragma unroll 8
;     for (int i = 0; i < 32; ++i) { const int kk = 2 * i + (lane >> 5); scr[kk * 33 + (lane & 31)] = W[(size_t)(k0 + kk) * N + n0 + (lane & 31)]; }
;     asm volatile("s_waitcnt lgkmcnt(0)" ::: "memory");
;     const int c = lane & 7;
;     float gk[8];
; #pragma unroll
;     for (int j = 0; j < 8; ++j) gk[j] = gain ? gain[k0 + 8 * c + j] : 1.0f;
; #pragma unroll
;     for (int j = 0; j < 4; ++j) { const int n = (lane >> 3) + 8 * j; const LAS float* s = scr + (8 * c) * 33 + n;
;         u32x4 o; o.x = cvt_pk_bf16(s[0 * 33] * gk[0], s[1 * 33] * gk[1]); o.y = cvt_pk_bf16(s[2 * 33] * gk[2], s[3 * 33] * gk[3]);
;         o.z = cvt_pk_bf16(s[4 * 33] * gk[4], s[5 * 33] * gk[5]); o.w = cvt_pk_bf16(s[6 * 33] * gk[6], s[7 * 33] * gk[7]);
;         const int ng = n0 + n; int drow = ng;
;         if (MAP == 1) { const int half = ng / DFF, r = ng % DFF; drow = (r / 128) * 256 + half * 128 + (r % 128); }
;         if (MAP == 2) { drow = ng < 1536 ? ng + 1024 : (ng < 2560 ? ng - 1536 : ng); }
;         *(u32x4*)(Wt + (size_t)drow * ldk + k0 + 8 * c) = o; }
;     asm volatile("s_waitcnt lgkmcnt(0)" ::: "memory");
.LBB0_929:
	v_lshl_add_u64 v[66:67], v[64:65], 0, s[30:31]
	global_load_dword v192, v[66:67], off
	v_lshl_add_u64 v[66:67], v[62:63], 0, s[30:31]
	global_load_dword v193, v[66:67], off
	v_lshl_add_u64 v[66:67], v[60:61], 0, s[30:31]
	global_load_dword v194, v[66:67], off
	v_lshl_add_u64 v[66:67], v[58:59], 0, s[30:31]
	global_load_dword v195, v[66:67], off
	v_lshl_add_u64 v[66:67], v[56:57], 0, s[30:31]
	global_load_dword v196, v[66:67], off
	v_lshl_add_u64 v[66:67], v[54:55], 0, s[30:31]
	global_load_dword v197, v[66:67], off
	v_lshl_add_u64 v[66:67], v[52:53], 0, s[30:31]
	global_load_dword v198, v[66:67], off
	v_lshl_add_u64 v[66:67], v[50:51], 0, s[30:31]
	global_load_dword v199, v[66:67], off
	s_add_u32 s30, s30, 0x10000
	s_addc_u32 s31, s31, 0
	v_lshl_add_u64 v[66:67], v[64:65], 0, s[30:31]
	global_load_dword v200, v[66:67], off
	v_lshl_add_u64 v[66:67], v[62:63], 0, s[30:31]
	global_load_dword v201, v[66:67], off
	v_lshl_add_u64 v[66:67], v[60:61], 0, s[30:31]
	global_load_dword v202, v[66:67], off
	v_lshl_add_u64 v[66:67], v[58:59], 0, s[30:31]
	global_load_dword v203, v[66:67], off
	v_lshl_add_u64 v[66:67], v[56:57], 0, s[30:31]
	global_load_dword v204, v[66:67], off
	v_lshl_add_u64 v[66:67], v[54:55], 0, s[30:31]
	global_load_dword v205, v[66:67], off
	v_lshl_add_u64 v[66:67], v[52:53], 0, s[30:31]
	global_load_dword v206, v[66:67], off
	v_lshl_add_u64 v[66:67], v[50:51], 0, s[30:31]
	global_load_dword v207, v[66:67], off
	s_add_u32 s30, s30, 0x10000
	s_addc_u32 s31, s31, 0
	v_lshl_add_u64 v[66:67], v[64:65], 0, s[30:31]
	global_load_dword v208, v[66:67], off
	v_lshl_add_u64 v[66:67], v[62:63], 0, s[30:31]
	global_load_dword v209, v[66:67], off
	v_lshl_add_u64 v[66:67], v[60:61], 0, s[30:31]
	global_load_dword v210, v[66:67], off
	v_lshl_add_u64 v[66:67], v[58:59], 0, s[30:31]
	global_load_dword v211, v[66:67], off
	v_lshl_add_u64 v[66:67], v[56:57], 0, s[30:31]
	global_load_dword v212, v[66:67], off
	v_lshl_add_u64 v[66:67], v[54:55], 0, s[30:31]
	global_load_dword v213, v[66:67], off
	v_lshl_add_u64 v[66:67], v[52:53], 0, s[30:31]
	global_load_dword v214, v[66:67], off
	v_lshl_add_u64 v[66:67], v[50:51], 0, s[30:31]
	global_load_dword v215, v[66:67], off
	s_add_u32 s30, s30, 0x10000
	s_addc_u32 s31, s31, 0
	v_lshl_add_u64 v[66:67], v[64:65], 0, s[30:31]
	global_load_dword v216, v[66:67], off
	v_lshl_add_u64 v[66:67], v[62:63], 0, s[30:31]
	global_load_dword v217, v[66:67], off
	v_lshl_add_u64 v[66:67], v[60:61], 0, s[30:31]
	global_load_dword v218, v[66:67], off
	v_lshl_add_u64 v[66:67], v[58:59], 0, s[30:31]
	global_load_dword v219, v[66:67], off
	v_lshl_add_u64 v[66:67], v[56:57], 0, s[30:31]
	global_load_dword v220, v[66:67], off
	v_lshl_add_u64 v[66:67], v[54:55], 0, s[30:31]
	global_load_dword v221, v[66:67], off
	v_lshl_add_u64 v[66:67], v[52:53], 0, s[30:31]
	global_load_dword v222, v[66:67], off
	v_lshl_add_u64 v[66:67], v[50:51], 0, s[30:31]
	global_load_dword v223, v[66:67], off
	s_add_u32 s30, s30, 0x10000
	s_addc_u32 s31, s31, 0
	s_waitcnt vmcnt(24)
	ds_write_b32 v39, v192
	ds_write_b32 v39, v193 offset:264
	ds_write_b32 v39, v194 offset:528
	ds_write_b32 v39, v195 offset:792
	ds_write_b32 v39, v196 offset:1056
	ds_write_b32 v39, v197 offset:1320
	ds_write_b32 v39, v198 offset:1584
	ds_write_b32 v39, v199 offset:1848
	v_add_u32_e32 v39, 0x840, v39
	s_waitcnt vmcnt(16)
	ds_write_b32 v39, v200
	ds_write_b32 v39, v201 offset:264
	ds_write_b32 v39, v202 offset:528
	ds_write_b32 v39, v203 offset:792
	ds_write_b32 v39, v204 offset:1056
	ds_write_b32 v39, v205 offset:1320
	ds_write_b32 v39, v206 offset:1584
	ds_write_b32 v39, v207 offset:1848
	v_add_u32_e32 v39, 0x840, v39
	s_waitcnt vmcnt(8)
	ds_write_b32 v39, v208
	ds_write_b32 v39, v209 offset:264
	ds_write_b32 v39, v210 offset:528
	ds_write_b32 v39, v211 offset:792
	ds_write_b32 v39, v212 offset:1056
	ds_write_b32 v39, v213 offset:1320
	ds_write_b32 v39, v214 offset:1584
	ds_write_b32 v39, v215 offset:1848
	v_add_u32_e32 v39, 0x840, v39
	s_waitcnt vmcnt(0)
	ds_write_b32 v39, v216
	ds_write_b32 v39, v217 offset:264
	ds_write_b32 v39, v218 offset:528
	ds_write_b32 v39, v219 offset:792
	ds_write_b32 v39, v220 offset:1056
	ds_write_b32 v39, v221 offset:1320
	ds_write_b32 v39, v222 offset:1584
	ds_write_b32 v39, v223 offset:1848
	v_add_u32_e32 v39, 0x840, v39
	v_lshl_add_u32 v39, v1, 1, v185
	v_lshlrev_b32_e32 v41, 5, v1
	s_waitcnt lgkmcnt(0)
	v_and_b32_e32 v39, 0x1ffc0, v39
	v_and_b32_e32 v41, 0x3e0, v41
	ds_read2_b32 v[50:51], v71 offset1:33
	v_mov_b32_e32 v55, v0
	v_lshlrev_b32_e32 v54, 1, v39
	v_or_b32_e32 v39, v41, v70
	s_waitcnt lgkmcnt(0)
	v_cvt_pk_bf16_f32 v50, v50, v51
	ds_read2_b32 v[52:53], v71 offset0:66 offset1:99
	v_mov_b32_e32 v57, v0
	v_lshl_add_u64 v[54:55], v[2:3], 0, v[54:55]
	v_lshlrev_b32_e32 v56, 11, v39
	s_waitcnt lgkmcnt(0)
	v_cvt_pk_bf16_f32 v51, v52, v53
	ds_read2_b32 v[52:53], v71 offset0:132 offset1:165
	v_lshl_add_u64 v[56:57], v[54:55], 0, v[56:57]
	s_waitcnt lgkmcnt(0)
	v_cvt_pk_bf16_f32 v52, v52, v53
	ds_read2_b32 v[58:59], v71 offset0:198 offset1:231
	s_waitcnt lgkmcnt(0)
	v_cvt_pk_bf16_f32 v53, v58, v59
	flat_store_dwordx4 v[56:57], v[50:53]
	ds_read2_b32 v[50:51], v71 offset0:8 offset1:41
	v_or_b32_e32 v39, v41, v72
	s_waitcnt lgkmcnt(0)
	v_cvt_pk_bf16_f32 v50, v50, v51
	ds_read2_b32 v[52:53], v71 offset0:74 offset1:107
	v_mov_b32_e32 v59, v0
	v_lshlrev_b32_e32 v58, 11, v39
	s_waitcnt lgkmcnt(0)
	v_cvt_pk_bf16_f32 v51, v52, v53
	ds_read2_b32 v[52:53], v71 offset0:140 offset1:173
	v_lshl_add_u64 v[58:59], v[54:55], 0, v[58:59]
	s_waitcnt lgkmcnt(0)
	v_cvt_pk_bf16_f32 v52, v52, v53
	ds_read2_b32 v[56:57], v71 offset0:206 offset1:239
	s_waitcnt lgkmcnt(0)
	v_cvt_pk_bf16_f32 v53, v56, v57
	flat_store_dwordx4 v[58:59], v[50:53]
	ds_read2_b32 v[50:51], v71 offset0:16 offset1:49
	v_or_b32_e32 v39, v41, v73
	s_waitcnt lgkmcnt(0)
	v_cvt_pk_bf16_f32 v50, v50, v51
	ds_read2_b32 v[52:53], v71 offset0:82 offset1:115
	v_mov_b32_e32 v59, v0
	v_lshlrev_b32_e32 v58, 11, v39
	s_waitcnt lgkmcnt(0)
	v_cvt_pk_bf16_f32 v51, v52, v53
	ds_read2_b32 v[52:53], v71 offset0:148 offset1:181
	v_lshl_add_u64 v[58:59], v[54:55], 0, v[58:59]
	s_waitcnt lgkmcnt(0)
	v_cvt_pk_bf16_f32 v52, v52, v53
	ds_read2_b32 v[56:57], v71 offset0:214 offset1:247
	s_waitcnt lgkmcnt(0)
	v_cvt_pk_bf16_f32 v53, v56, v57
	flat_store_dwordx4 v[58:59], v[50:53]
	ds_read2_b32 v[50:51], v71 offset0:24 offset1:57
	v_or_b32_e32 v39, v41, v74
	s_waitcnt lgkmcnt(0)
	v_cvt_pk_bf16_f32 v50, v50, v51
	ds_read2_b32 v[52:53], v71 offset0:90 offset1:123
	v_mov_b32_e32 v59, v0
	v_lshlrev_b32_e32 v58, 11, v39
	s_waitcnt lgkmcnt(0)
	v_cvt_pk_bf16_f32 v51, v52, v53
	ds_read2_b32 v[52:53], v71 offset0:156 offset1:189
	v_lshl_add_u64 v[54:55], v[54:55], 0, v[58:59]
	s_waitcnt lgkmcnt(0)
	v_cvt_pk_bf16_f32 v52, v52, v53
	ds_read2_b32 v[56:57], v71 offset0:222 offset1:255
	s_waitcnt lgkmcnt(0)
	v_cvt_pk_bf16_f32 v53, v56, v57
	flat_store_dwordx4 v[54:55], v[50:53]
	s_waitcnt lgkmcnt(0)

; #define LAS __attribute__((address_space(3)))
; __device__ __forceinline__ unsigned cvt_pk_bf16(float lo, float hi) { unsigned r; asm volatile("v_cvt_pk_bf16_f32 %0, %1, %2" : "=v"(r) : "v"(lo), "v"(hi)); return r; }
; template <int MAP>
; __device__ __forceinline__ void cvt_item(const float* W, int K, int N, bf16_t* Wt, int ldk, const float* gain, LAS float* scr, int item, int lane) {
;     ...
; #pragma unroll 8
;     for (int i = 0; i < 32; ++i) { const int kk = 2 * i + (lane >> 5); scr[kk * 33 + (lane & 31)] = W[(size_t)(k0 + kk) * N + n0 + (lane & 31)]; }
;     asm volatile("s_waitcnt lgkmcnt(0)" ::: "memory");
;     const int c = lane & 7;
;     float gk[8];
; #pragma unroll
;     for (int j = 0; j < 8; ++j) gk[j] = gain ? gain[k0 + 8 * c + j] : 1.0f;
; #pragma unroll
;     for (int j = 0; j < 4; ++j) { const int n = (lane >> 3) + 8 * j; const LAS float* s = scr + (8 * c) * 33 + n;
;         u32x4 o; o.x = cvt_pk_bf16(s[0 * 33] * gk[0], s[1 * 33] * gk[1]); o.y = cvt_pk_bf16(s[2 * 33] * gk[2], s[3 * 33] * gk[3]);
;         o.z = cvt_pk_bf16(s[4 * 33] * gk[4], s[5 * 33] * gk[5]); o.w = cvt_pk_bf16(s[6 * 33] * gk[6], s[7 * 33] * gk[7]);
;         const int ng = n0 + n; int drow = ng;
;         if (MAP == 1) { const int half = ng / DFF, r = ng % DFF; drow = (r / 128) * 256 + half * 128 + (r % 128); }
;         if (MAP == 2) { drow = ng < 1536 ? ng + 1024 : (ng < 2560 ? ng - 1536 : ng); }
;         *(u32x4*)(Wt + (size_t)drow * ldk + k0 + 8 * c) = o; }
;     asm volatile("s_waitcnt lgkmcnt(0)" ::: "memory");
.LBB0_934:
	v_lshl_add_u64 v[66:67], v[64:65], 0, s[28:29]
	global_load_dword v192, v[66:67], off
	v_lshl_add_u64 v[66:67], v[62:63], 0, s[28:29]
	global_load_dword v193, v[66:67], off
	v_lshl_add_u64 v[66:67], v[60:61], 0, s[28:29]
	global_load_dword v194, v[66:67], off
	v_lshl_add_u64 v[66:67], v[58:59], 0, s[28:29]
	global_load_dword v195, v[66:67], off
	v_lshl_add_u64 v[66:67], v[56:57], 0, s[28:29]
	global_load_dword v196, v[66:67], off
	v_lshl_add_u64 v[66:67], v[54:55], 0, s[28:29]
	global_load_dword v197, v[66:67], off
	v_lshl_add_u64 v[66:67], v[52:53], 0, s[28:29]
	global_load_dword v198, v[66:67], off
	v_lshl_add_u64 v[66:67], v[50:51], 0, s[28:29]
	global_load_dword v199, v[66:67], off
	s_add_u32 s28, s28, 0x10000
	s_addc_u32 s29, s29, 0
	v_lshl_add_u64 v[66:67], v[64:65], 0, s[28:29]
	global_load_dword v200, v[66:67], off
	v_lshl_add_u64 v[66:67], v[62:63], 0, s[28:29]
	global_load_dword v201, v[66:67], off
	v_lshl_add_u64 v[66:67], v[60:61], 0, s[28:29]
	global_load_dword v202, v[66:67], off
	v_lshl_add_u64 v[66:67], v[58:59], 0, s[28:29]
	global_load_dword v203, v[66:67], off
	v_lshl_add_u64 v[66:67], v[56:57], 0, s[28:29]
	global_load_dword v204, v[66:67], off
	v_lshl_add_u64 v[66:67], v[54:55], 0, s[28:29]
	global_load_dword v205, v[66:67], off
	v_lshl_add_u64 v[66:67], v[52:53], 0, s[28:29]
	global_load_dword v206, v[66:67], off
	v_lshl_add_u64 v[66:67], v[50:51], 0, s[28:29]
	global_load_dword v207, v[66:67], off
	s_add_u32 s28, s28, 0x10000
	s_addc_u32 s29, s29, 0
	v_lshl_add_u64 v[66:67], v[64:65], 0, s[28:29]
	global_load_dword v208, v[66:67], off
	v_lshl_add_u64 v[66:67], v[62:63], 0, s[28:29]
	global_load_dword v209, v[66:67], off
	v_lshl_add_u64 v[66:67], v[60:61], 0, s[28:29]
	global_load_dword v210, v[66:67], off
	v_lshl_add_u64 v[66:67], v[58:59], 0, s[28:29]
	global_load_dword v211, v[66:67], off
	v_lshl_add_u64 v[66:67], v[56:57], 0, s[28:29]
	global_load_dword v212, v[66:67], off
	v_lshl_add_u64 v[66:67], v[54:55], 0, s[28:29]
	global_load_dword v213, v[66:67], off
	v_lshl_add_u64 v[66:67], v[52:53], 0, s[28:29]
	global_load_dword v214, v[66:67], off
	v_lshl_add_u64 v[66:67], v[50:51], 0, s[28:29]
	global_load_dword v215, v[66:67], off
	s_add_u32 s28, s28, 0x10000
	s_addc_u32 s29, s29, 0
	v_lshl_add_u64 v[66:67], v[64:65], 0, s[28:29]
	global_load_dword v216, v[66:67], off
	v_lshl_add_u64 v[66:67], v[62:63], 0, s[28:29]
	global_load_dword v217, v[66:67], off
	v_lshl_add_u64 v[66:67], v[60:61], 0, s[28:29]
	global_load_dword v218, v[66:67], off
	v_lshl_add_u64 v[66:67], v[58:59], 0, s[28:29]
	global_load_dword v219, v[66:67], off
	v_lshl_add_u64 v[66:67], v[56:57], 0, s[28:29]
	global_load_dword v220, v[66:67], off
	v_lshl_add_u64 v[66:67], v[54:55], 0, s[28:29]
	global_load_dword v221, v[66:67], off
	v_lshl_add_u64 v[66:67], v[52:53], 0, s[28:29]
	global_load_dword v222, v[66:67], off
	v_lshl_add_u64 v[66:67], v[50:51], 0, s[28:29]
	global_load_dword v223, v[66:67], off
	s_add_u32 s28, s28, 0x10000
	s_addc_u32 s29, s29, 0
	s_waitcnt vmcnt(24)
	ds_write_b32 v39, v192
	ds_write_b32 v39, v193 offset:264
	ds_write_b32 v39, v194 offset:528
	ds_write_b32 v39, v195 offset:792
	ds_write_b32 v39, v196 offset:1056
	ds_write_b32 v39, v197 offset:1320
	ds_write_b32 v39, v198 offset:1584
	ds_write_b32 v39, v199 offset:1848
	v_add_u32_e32 v39, 0x840, v39
	s_waitcnt vmcnt(16)
	ds_write_b32 v39, v200
	ds_write_b32 v39, v201 offset:264
	ds_write_b32 v39, v202 offset:528
	ds_write_b32 v39, v203 offset:792
	ds_write_b32 v39, v204 offset:1056
	ds_write_b32 v39, v205 offset:1320
	ds_write_b32 v39, v206 offset:1584
	ds_write_b32 v39, v207 offset:1848
	v_add_u32_e32 v39, 0x840, v39
	s_waitcnt vmcnt(8)
	ds_write_b32 v39, v208
	ds_write_b32 v39, v209 offset:264
	ds_write_b32 v39, v210 offset:528
	ds_write_b32 v39, v211 offset:792
	ds_write_b32 v39, v212 offset:1056
	ds_write_b32 v39, v213 offset:1320
	ds_write_b32 v39, v214 offset:1584
	ds_write_b32 v39, v215 offset:1848
	v_add_u32_e32 v39, 0x840, v39
	s_waitcnt vmcnt(0)
	ds_write_b32 v39, v216
	ds_write_b32 v39, v217 offset:264
	ds_write_b32 v39, v218 offset:528
	ds_write_b32 v39, v219 offset:792
	ds_write_b32 v39, v220 offset:1056
	ds_write_b32 v39, v221 offset:1320
	ds_write_b32 v39, v222 offset:1584
	ds_write_b32 v39, v223 offset:1848
	v_add_u32_e32 v39, 0x840, v39
	v_lshl_add_u32 v39, v1, 1, v186
	v_lshlrev_b32_e32 v41, 5, v1
	s_waitcnt lgkmcnt(0)
	v_and_b32_e32 v39, 0x1ffc0, v39
	v_and_b32_e32 v41, 0x3e0, v41
	ds_read2_b32 v[50:51], v71 offset1:33
	v_mov_b32_e32 v55, v0
	v_lshlrev_b32_e32 v54, 1, v39
	v_or_b32_e32 v39, v41, v70
	s_waitcnt lgkmcnt(0)
	v_cvt_pk_bf16_f32 v50, v50, v51
	ds_read2_b32 v[52:53], v71 offset0:66 offset1:99
	v_mov_b32_e32 v57, v0
	v_lshl_add_u64 v[54:55], v[4:5], 0, v[54:55]
	v_lshlrev_b32_e32 v56, 11, v39
	s_waitcnt lgkmcnt(0)
	v_cvt_pk_bf16_f32 v51, v52, v53
	ds_read2_b32 v[52:53], v71 offset0:132 offset1:165
	v_lshl_add_u64 v[56:57], v[54:55], 0, v[56:57]
	s_waitcnt lgkmcnt(0)
	v_cvt_pk_bf16_f32 v52, v52, v53
	ds_read2_b32 v[58:59], v71 offset0:198 offset1:231
	s_waitcnt lgkmcnt(0)
	v_cvt_pk_bf16_f32 v53, v58, v59
	flat_store_dwordx4 v[56:57], v[50:53]
	ds_read2_b32 v[50:51], v71 offset0:8 offset1:41
	v_or_b32_e32 v39, v41, v72
	s_waitcnt lgkmcnt(0)
	v_cvt_pk_bf16_f32 v50, v50, v51
	ds_read2_b32 v[52:53], v71 offset0:74 offset1:107
	v_mov_b32_e32 v59, v0
	v_lshlrev_b32_e32 v58, 11, v39
	s_waitcnt lgkmcnt(0)
	v_cvt_pk_bf16_f32 v51, v52, v53
	ds_read2_b32 v[52:53], v71 offset0:140 offset1:173
	v_lshl_add_u64 v[58:59], v[54:55], 0, v[58:59]
	s_waitcnt lgkmcnt(0)
	v_cvt_pk_bf16_f32 v52, v52, v53
	ds_read2_b32 v[56:57], v71 offset0:206 offset1:239
	s_waitcnt lgkmcnt(0)
	v_cvt_pk_bf16_f32 v53, v56, v57
	flat_store_dwordx4 v[58:59], v[50:53]
	ds_read2_b32 v[50:51], v71 offset0:16 offset1:49
	v_or_b32_e32 v39, v41, v73
	s_waitcnt lgkmcnt(0)
	v_cvt_pk_bf16_f32 v50, v50, v51
	ds_read2_b32 v[52:53], v71 offset0:82 offset1:115
	v_mov_b32_e32 v59, v0
	v_lshlrev_b32_e32 v58, 11, v39
	s_waitcnt lgkmcnt(0)
	v_cvt_pk_bf16_f32 v51, v52, v53
	ds_read2_b32 v[52:53], v71 offset0:148 offset1:181
	v_lshl_add_u64 v[58:59], v[54:55], 0, v[58:59]
	s_waitcnt lgkmcnt(0)
	v_cvt_pk_bf16_f32 v52, v52, v53
	ds_read2_b32 v[56:57], v71 offset0:214 offset1:247
	s_waitcnt lgkmcnt(0)
	v_cvt_pk_bf16_f32 v53, v56, v57
	flat_store_dwordx4 v[58:59], v[50:53]
	ds_read2_b32 v[50:51], v71 offset0:24 offset1:57
	v_or_b32_e32 v39, v41, v74
	s_waitcnt lgkmcnt(0)
	v_cvt_pk_bf16_f32 v50, v50, v51
	ds_read2_b32 v[52:53], v71 offset0:90 offset1:123
	v_mov_b32_e32 v59, v0
	v_lshlrev_b32_e32 v58, 11, v39
	s_waitcnt lgkmcnt(0)
	v_cvt_pk_bf16_f32 v51, v52, v53
	ds_read2_b32 v[52:53], v71 offset0:156 offset1:189
	v_lshl_add_u64 v[54:55], v[54:55], 0, v[58:59]
	s_waitcnt lgkmcnt(0)
	v_cvt_pk_bf16_f32 v52, v52, v53
	ds_read2_b32 v[56:57], v71 offset0:222 offset1:255
	s_waitcnt lgkmcnt(0)
	v_cvt_pk_bf16_f32 v53, v56, v57
	flat_store_dwordx4 v[54:55], v[50:53]
	s_waitcnt lgkmcnt(0)

; #define LAS __attribute__((address_space(3)))
; __device__ __forceinline__ unsigned cvt_pk_bf16(float lo, float hi) { unsigned r; asm volatile("v_cvt_pk_bf16_f32 %0, %1, %2" : "=v"(r) : "v"(lo), "v"(hi)); return r; }
; template <int MAP>
; __device__ __forceinline__ void cvt_item(const float* W, int K, int N, bf16_t* Wt, int ldk, const float* gain, LAS float* scr, int item, int lane) {
;     ...
; #pragma unroll 8
;     for (int i = 0; i < 32; ++i) { const int kk = 2 * i + (lane >> 5); scr[kk * 33 + (lane & 31)] = W[(size_t)(k0 + kk) * N + n0 + (lane & 31)]; }
;     asm volatile("s_waitcnt lgkmcnt(0)" ::: "memory");
;     const int c = lane & 7;
;     float gk[8];
; #pragma unroll
;     for (int j = 0; j < 8; ++j) gk[j] = gain ? gain[k0 + 8 * c + j] : 1.0f;
; #pragma unroll
;     for (int j = 0; j < 4; ++j) { const int n = (lane >> 3) + 8 * j; const LAS float* s = scr + (8 * c) * 33 + n;
;         u32x4 o; o.x = cvt_pk_bf16(s[0 * 33] * gk[0], s[1 * 33] * gk[1]); o.y = cvt_pk_bf16(s[2 * 33] * gk[2], s[3 * 33] * gk[3]);
;         o.z = cvt_pk_bf16(s[4 * 33] * gk[4], s[5 * 33] * gk[5]); o.w = cvt_pk_bf16(s[6 * 33] * gk[6], s[7 * 33] * gk[7]);
;         const int ng = n0 + n; int drow = ng;
;         if (MAP == 1) { const int half = ng / DFF, r = ng % DFF; drow = (r / 128) * 256 + half * 128 + (r % 128); }
;         if (MAP == 2) { drow = ng < 1536 ? ng + 1024 : (ng < 2560 ? ng - 1536 : ng); }
;         *(u32x4*)(Wt + (size_t)drow * ldk + k0 + 8 * c) = o; }
;     asm volatile("s_waitcnt lgkmcnt(0)" ::: "memory");
.LBB0_939:
	v_lshl_add_u64 v[66:67], v[64:65], 0, s[26:27]
	global_load_dword v192, v[66:67], off
	v_lshl_add_u64 v[66:67], v[62:63], 0, s[26:27]
	global_load_dword v193, v[66:67], off
	v_lshl_add_u64 v[66:67], v[60:61], 0, s[26:27]
	global_load_dword v194, v[66:67], off
	v_lshl_add_u64 v[66:67], v[58:59], 0, s[26:27]
	global_load_dword v195, v[66:67], off
	v_lshl_add_u64 v[66:67], v[56:57], 0, s[26:27]
	global_load_dword v196, v[66:67], off
	v_lshl_add_u64 v[66:67], v[54:55], 0, s[26:27]
	global_load_dword v197, v[66:67], off
	v_lshl_add_u64 v[66:67], v[52:53], 0, s[26:27]
	global_load_dword v198, v[66:67], off
	v_lshl_add_u64 v[66:67], v[50:51], 0, s[26:27]
	global_load_dword v199, v[66:67], off
	s_add_u32 s26, s26, 0x10000
	s_addc_u32 s27, s27, 0
	v_lshl_add_u64 v[66:67], v[64:65], 0, s[26:27]
	global_load_dword v200, v[66:67], off
	v_lshl_add_u64 v[66:67], v[62:63], 0, s[26:27]
	global_load_dword v201, v[66:67], off
	v_lshl_add_u64 v[66:67], v[60:61], 0, s[26:27]
	global_load_dword v202, v[66:67], off
	v_lshl_add_u64 v[66:67], v[58:59], 0, s[26:27]
	global_load_dword v203, v[66:67], off
	v_lshl_add_u64 v[66:67], v[56:57], 0, s[26:27]
	global_load_dword v204, v[66:67], off
	v_lshl_add_u64 v[66:67], v[54:55], 0, s[26:27]
	global_load_dword v205, v[66:67], off
	v_lshl_add_u64 v[66:67], v[52:53], 0, s[26:27]
	global_load_dword v206, v[66:67], off
	v_lshl_add_u64 v[66:67], v[50:51], 0, s[26:27]
	global_load_dword v207, v[66:67], off
	s_add_u32 s26, s26, 0x10000
	s_addc_u32 s27, s27, 0
	v_lshl_add_u64 v[66:67], v[64:65], 0, s[26:27]
	global_load_dword v208, v[66:67], off
	v_lshl_add_u64 v[66:67], v[62:63], 0, s[26:27]
	global_load_dword v209, v[66:67], off
	v_lshl_add_u64 v[66:67], v[60:61], 0, s[26:27]
	global_load_dword v210, v[66:67], off
	v_lshl_add_u64 v[66:67], v[58:59], 0, s[26:27]
	global_load_dword v211, v[66:67], off
	v_lshl_add_u64 v[66:67], v[56:57], 0, s[26:27]
	global_load_dword v212, v[66:67], off
	v_lshl_add_u64 v[66:67], v[54:55], 0, s[26:27]
	global_load_dword v213, v[66:67], off
	v_lshl_add_u64 v[66:67], v[52:53], 0, s[26:27]
	global_load_dword v214, v[66:67], off
	v_lshl_add_u64 v[66:67], v[50:51], 0, s[26:27]
	global_load_dword v215, v[66:67], off
	s_add_u32 s26, s26, 0x10000
	s_addc_u32 s27, s27, 0
	v_lshl_add_u64 v[66:67], v[64:65], 0, s[26:27]
	global_load_dword v216, v[66:67], off
	v_lshl_add_u64 v[66:67], v[62:63], 0, s[26:27]
	global_load_dword v217, v[66:67], off
	v_lshl_add_u64 v[66:67], v[60:61], 0, s[26:27]
	global_load_dword v218, v[66:67], off
	v_lshl_add_u64 v[66:67], v[58:59], 0, s[26:27]
	global_load_dword v219, v[66:67], off
	v_lshl_add_u64 v[66:67], v[56:57], 0, s[26:27]
	global_load_dword v220, v[66:67], off
	v_lshl_add_u64 v[66:67], v[54:55], 0, s[26:27]
	global_load_dword v221, v[66:67], off
	v_lshl_add_u64 v[66:67], v[52:53], 0, s[26:27]
	global_load_dword v222, v[66:67], off
	v_lshl_add_u64 v[66:67], v[50:51], 0, s[26:27]
	global_load_dword v223, v[66:67], off
	s_add_u32 s26, s26, 0x10000
	s_addc_u32 s27, s27, 0
	s_waitcnt vmcnt(24)
	ds_write_b32 v39, v192
	ds_write_b32 v39, v193 offset:264
	ds_write_b32 v39, v194 offset:528
	ds_write_b32 v39, v195 offset:792
	ds_write_b32 v39, v196 offset:1056
	ds_write_b32 v39, v197 offset:1320
	ds_write_b32 v39, v198 offset:1584
	ds_write_b32 v39, v199 offset:1848
	v_add_u32_e32 v39, 0x840, v39
	s_waitcnt vmcnt(16)
	ds_write_b32 v39, v200
	ds_write_b32 v39, v201 offset:264
	ds_write_b32 v39, v202 offset:528
	ds_write_b32 v39, v203 offset:792
	ds_write_b32 v39, v204 offset:1056
	ds_write_b32 v39, v205 offset:1320
	ds_write_b32 v39, v206 offset:1584
	ds_write_b32 v39, v207 offset:1848
	v_add_u32_e32 v39, 0x840, v39
	s_waitcnt vmcnt(8)
	ds_write_b32 v39, v208
	ds_write_b32 v39, v209 offset:264
	ds_write_b32 v39, v210 offset:528
	ds_write_b32 v39, v211 offset:792
	ds_write_b32 v39, v212 offset:1056
	ds_write_b32 v39, v213 offset:1320
	ds_write_b32 v39, v214 offset:1584
	ds_write_b32 v39, v215 offset:1848
	v_add_u32_e32 v39, 0x840, v39
	s_waitcnt vmcnt(0)
	ds_write_b32 v39, v216
	ds_write_b32 v39, v217 offset:264
	ds_write_b32 v39, v218 offset:528
	ds_write_b32 v39, v219 offset:792
	ds_write_b32 v39, v220 offset:1056
	ds_write_b32 v39, v221 offset:1320
	ds_write_b32 v39, v222 offset:1584
	ds_write_b32 v39, v223 offset:1848
	v_add_u32_e32 v39, 0x840, v39
	v_lshl_add_u32 v39, v1, 1, v187
	v_lshlrev_b32_e32 v41, 5, v1
	s_waitcnt lgkmcnt(0)
	v_and_b32_e32 v39, 0x1ffc0, v39
	v_and_b32_e32 v41, 0x3e0, v41
	ds_read2_b32 v[50:51], v71 offset1:33
	v_mov_b32_e32 v55, v0
	v_lshlrev_b32_e32 v54, 1, v39
	v_or_b32_e32 v39, v41, v70
	s_waitcnt lgkmcnt(0)
	v_cvt_pk_bf16_f32 v50, v50, v51
	ds_read2_b32 v[52:53], v71 offset0:66 offset1:99
	v_mov_b32_e32 v57, v0
	v_lshl_add_u64 v[54:55], v[6:7], 0, v[54:55]
	v_lshlrev_b32_e32 v56, 11, v39
	s_waitcnt lgkmcnt(0)
	v_cvt_pk_bf16_f32 v51, v52, v53
	ds_read2_b32 v[52:53], v71 offset0:132 offset1:165
	v_lshl_add_u64 v[56:57], v[54:55], 0, v[56:57]
	s_waitcnt lgkmcnt(0)
	v_cvt_pk_bf16_f32 v52, v52, v53
	ds_read2_b32 v[58:59], v71 offset0:198 offset1:231
	s_waitcnt lgkmcnt(0)
	v_cvt_pk_bf16_f32 v53, v58, v59
	flat_store_dwordx4 v[56:57], v[50:53]
	ds_read2_b32 v[50:51], v71 offset0:8 offset1:41
	v_or_b32_e32 v39, v41, v72
	s_waitcnt lgkmcnt(0)
	v_cvt_pk_bf16_f32 v50, v50, v51
	ds_read2_b32 v[52:53], v71 offset0:74 offset1:107
	v_mov_b32_e32 v59, v0
	v_lshlrev_b32_e32 v58, 11, v39
	s_waitcnt lgkmcnt(0)
	v_cvt_pk_bf16_f32 v51, v52, v53
	ds_read2_b32 v[52:53], v71 offset0:140 offset1:173
	v_lshl_add_u64 v[58:59], v[54:55], 0, v[58:59]
	s_waitcnt lgkmcnt(0)
	v_cvt_pk_bf16_f32 v52, v52, v53
	ds_read2_b32 v[56:57], v71 offset0:206 offset1:239
	s_waitcnt lgkmcnt(0)
	v_cvt_pk_bf16_f32 v53, v56, v57
	flat_store_dwordx4 v[58:59], v[50:53]
	ds_read2_b32 v[50:51], v71 offset0:16 offset1:49
	v_or_b32_e32 v39, v41, v73
	s_waitcnt lgkmcnt(0)
	v_cvt_pk_bf16_f32 v50, v50, v51
	ds_read2_b32 v[52:53], v71 offset0:82 offset1:115
	v_mov_b32_e32 v59, v0
	v_lshlrev_b32_e32 v58, 11, v39
	s_waitcnt lgkmcnt(0)
	v_cvt_pk_bf16_f32 v51, v52, v53
	ds_read2_b32 v[52:53], v71 offset0:148 offset1:181
	v_lshl_add_u64 v[58:59], v[54:55], 0, v[58:59]
	s_waitcnt lgkmcnt(0)
	v_cvt_pk_bf16_f32 v52, v52, v53
	ds_read2_b32 v[56:57], v71 offset0:214 offset1:247
	s_waitcnt lgkmcnt(0)
	v_cvt_pk_bf16_f32 v53, v56, v57
	flat_store_dwordx4 v[58:59], v[50:53]
	ds_read2_b32 v[50:51], v71 offset0:24 offset1:57
	v_or_b32_e32 v39, v41, v74
	s_waitcnt lgkmcnt(0)
	v_cvt_pk_bf16_f32 v50, v50, v51
	ds_read2_b32 v[52:53], v71 offset0:90 offset1:123
	v_mov_b32_e32 v59, v0
	v_lshlrev_b32_e32 v58, 11, v39
	s_waitcnt lgkmcnt(0)
	v_cvt_pk_bf16_f32 v51, v52, v53
	ds_read2_b32 v[52:53], v71 offset0:156 offset1:189
	v_lshl_add_u64 v[54:55], v[54:55], 0, v[58:59]
	s_waitcnt lgkmcnt(0)
	v_cvt_pk_bf16_f32 v52, v52, v53
	ds_read2_b32 v[56:57], v71 offset0:222 offset1:255
	s_waitcnt lgkmcnt(0)
	v_cvt_pk_bf16_f32 v53, v56, v57
	flat_store_dwordx4 v[54:55], v[50:53]
	s_waitcnt lgkmcnt(0)

; template <int MAP>
; __device__ __forceinline__ void cvt_item(const float* W, int K, int N, bf16_t* Wt, int ldk, const float* gain, LAS float* scr, int item, int lane) {
;     ...
; #pragma unroll 8
;     for (int i = 0; i < 32; ++i) { const int kk = 2 * i + (lane >> 5); scr[kk * 33 + (lane & 31)] = W[(size_t)(k0 + kk) * N + n0 + (lane & 31)]; }
;     asm volatile("s_waitcnt lgkmcnt(0)" ::: "memory");
.LBB0_944:
	v_lshl_add_u64 v[66:67], v[64:65], 0, s[24:25]
	global_load_dword v192, v[66:67], off
	v_lshl_add_u64 v[66:67], v[62:63], 0, s[24:25]
	global_load_dword v193, v[66:67], off
	v_lshl_add_u64 v[66:67], v[60:61], 0, s[24:25]
	global_load_dword v194, v[66:67], off
	v_lshl_add_u64 v[66:67], v[58:59], 0, s[24:25]
	global_load_dword v195, v[66:67], off
	v_lshl_add_u64 v[66:67], v[56:57], 0, s[24:25]
	global_load_dword v196, v[66:67], off
	v_lshl_add_u64 v[66:67], v[54:55], 0, s[24:25]
	global_load_dword v197, v[66:67], off
	v_lshl_add_u64 v[66:67], v[52:53], 0, s[24:25]
	global_load_dword v198, v[66:67], off
	v_lshl_add_u64 v[66:67], v[50:51], 0, s[24:25]
	global_load_dword v199, v[66:67], off
	s_add_u32 s24, s24, 0x10000
	s_addc_u32 s25, s25, 0
	v_lshl_add_u64 v[66:67], v[64:65], 0, s[24:25]
	global_load_dword v200, v[66:67], off
	v_lshl_add_u64 v[66:67], v[62:63], 0, s[24:25]
	global_load_dword v201, v[66:67], off
	v_lshl_add_u64 v[66:67], v[60:61], 0, s[24:25]
	global_load_dword v202, v[66:67], off
	v_lshl_add_u64 v[66:67], v[58:59], 0, s[24:25]
	global_load_dword v203, v[66:67], off
	v_lshl_add_u64 v[66:67], v[56:57], 0, s[24:25]
	global_load_dword v204, v[66:67], off
	v_lshl_add_u64 v[66:67], v[54:55], 0, s[24:25]
	global_load_dword v205, v[66:67], off
	v_lshl_add_u64 v[66:67], v[52:53], 0, s[24:25]
	global_load_dword v206, v[66:67], off
	v_lshl_add_u64 v[66:67], v[50:51], 0, s[24:25]
	global_load_dword v207, v[66:67], off
	s_add_u32 s24, s24, 0x10000
	s_addc_u32 s25, s25, 0
	v_lshl_add_u64 v[66:67], v[64:65], 0, s[24:25]
	global_load_dword v208, v[66:67], off
	v_lshl_add_u64 v[66:67], v[62:63], 0, s[24:25]
	global_load_dword v209, v[66:67], off
	v_lshl_add_u64 v[66:67], v[60:61], 0, s[24:25]
	global_load_dword v210, v[66:67], off
	v_lshl_add_u64 v[66:67], v[58:59], 0, s[24:25]
	global_load_dword v211, v[66:67], off
	v_lshl_add_u64 v[66:67], v[56:57], 0, s[24:25]
	global_load_dword v212, v[66:67], off
	v_lshl_add_u64 v[66:67], v[54:55], 0, s[24:25]
	global_load_dword v213, v[66:67], off
	v_lshl_add_u64 v[66:67], v[52:53], 0, s[24:25]
	global_load_dword v214, v[66:67], off
	v_lshl_add_u64 v[66:67], v[50:51], 0, s[24:25]
	global_load_dword v215, v[66:67], off
	s_add_u32 s24, s24, 0x10000
	s_addc_u32 s25, s25, 0
	v_lshl_add_u64 v[66:67], v[64:65], 0, s[24:25]
	global_load_dword v216, v[66:67], off
	v_lshl_add_u64 v[66:67], v[62:63], 0, s[24:25]
	global_load_dword v217, v[66:67], off
	v_lshl_add_u64 v[66:67], v[60:61], 0, s[24:25]
	global_load_dword v218, v[66:67], off
	v_lshl_add_u64 v[66:67], v[58:59], 0, s[24:25]
	global_load_dword v219, v[66:67], off
	v_lshl_add_u64 v[66:67], v[56:57], 0, s[24:25]
	global_load_dword v220, v[66:67], off
	v_lshl_add_u64 v[66:67], v[54:55], 0, s[24:25]
	global_load_dword v221, v[66:67], off
	v_lshl_add_u64 v[66:67], v[52:53], 0, s[24:25]
	global_load_dword v222, v[66:67], off
	v_lshl_add_u64 v[66:67], v[50:51], 0, s[24:25]
	global_load_dword v223, v[66:67], off
	s_add_u32 s24, s24, 0x10000
	s_addc_u32 s25, s25, 0
	s_waitcnt vmcnt(24)
	ds_write_b32 v39, v192
	ds_write_b32 v39, v193 offset:264
	ds_write_b32 v39, v194 offset:528
	ds_write_b32 v39, v195 offset:792
	ds_write_b32 v39, v196 offset:1056
	ds_write_b32 v39, v197 offset:1320
	ds_write_b32 v39, v198 offset:1584
	ds_write_b32 v39, v199 offset:1848
	v_add_u32_e32 v39, 0x840, v39
	s_waitcnt vmcnt(16)
	ds_write_b32 v39, v200
	ds_write_b32 v39, v201 offset:264
	ds_write_b32 v39, v202 offset:528
	ds_write_b32 v39, v203 offset:792
	ds_write_b32 v39, v204 offset:1056
	ds_write_b32 v39, v205 offset:1320
	ds_write_b32 v39, v206 offset:1584
	ds_write_b32 v39, v207 offset:1848
	v_add_u32_e32 v39, 0x840, v39
	s_waitcnt vmcnt(8)
; #define LAS __attribute__((address_space(3)))
; __device__ __forceinline__ unsigned cvt_pk_bf16(float lo, float hi) { unsigned r; asm volatile("v_cvt_pk_bf16_f32 %0, %1, %2" : "=v"(r) : "v"(lo), "v"(hi)); return r; }
; template <int MAP>
; __device__ __forceinline__ void cvt_item(const float* W, int K, int N, bf16_t* Wt, int ldk, const float* gain, LAS float* scr, int item, int lane) {
;     ...
;     for (int i = 0; i < 32; ++i) { const int kk = 2 * i + (lane >> 5); scr[kk * 33 + (lane & 31)] = W[(size_t)(k0 + kk) * N + n0 + (lane & 31)]; }
;     asm volatile("s_waitcnt lgkmcnt(0)" ::: "memory");
;     const int c = lane & 7;
;     float gk[8];
; #pragma unroll
;     for (int j = 0; j < 8; ++j) gk[j] = gain ? gain[k0 + 8 * c + j] : 1.0f;
; #pragma unroll
;     for (int j = 0; j < 4; ++j) { const int n = (lane >> 3) + 8 * j; const LAS float* s = scr + (8 * c) * 33 + n;
;         u32x4 o; o.x = cvt_pk_bf16(s[0 * 33] * gk[0], s[1 * 33] * gk[1]); o.y = cvt_pk_bf16(s[2 * 33] * gk[2], s[3 * 33] * gk[3]);
;         o.z = cvt_pk_bf16(s[4 * 33] * gk[4], s[5 * 33] * gk[5]); o.w = cvt_pk_bf16(s[6 * 33] * gk[6], s[7 * 33] * gk[7]);
;         const int ng = n0 + n; int drow = ng;
;         if (MAP == 1) { const int half = ng / DFF, r = ng % DFF; drow = (r / 128) * 256 + half * 128 + (r % 128); }
;         if (MAP == 2) { drow = ng < 1536 ? ng + 1024 : (ng < 2560 ? ng - 1536 : ng); }
;         *(u32x4*)(Wt + (size_t)drow * ldk + k0 + 8 * c) = o; }
;     asm volatile("s_waitcnt lgkmcnt(0)" ::: "memory");
	ds_write_b32 v39, v208
	ds_write_b32 v39, v209 offset:264
	ds_write_b32 v39, v210 offset:528
	ds_write_b32 v39, v211 offset:792
	ds_write_b32 v39, v212 offset:1056
	ds_write_b32 v39, v213 offset:1320
	ds_write_b32 v39, v214 offset:1584
	ds_write_b32 v39, v215 offset:1848
	v_add_u32_e32 v39, 0x840, v39
	s_waitcnt vmcnt(0)
	ds_write_b32 v39, v216
	ds_write_b32 v39, v217 offset:264
	ds_write_b32 v39, v218 offset:528
	ds_write_b32 v39, v219 offset:792
	ds_write_b32 v39, v220 offset:1056
	ds_write_b32 v39, v221 offset:1320
	ds_write_b32 v39, v222 offset:1584
	ds_write_b32 v39, v223 offset:1848
	v_add_u32_e32 v39, 0x840, v39
	v_lshl_add_u32 v39, v1, 1, v188
	v_lshlrev_b32_e32 v41, 5, v1
	v_and_b32_e32 v39, 0x1ffc0, v39
	v_and_b32_e32 v41, 0x3e0, v41
	s_waitcnt lgkmcnt(0)
	v_lshlrev_b32_e32 v54, 1, v39
	v_or_b32_e32 v39, v41, v70
	ds_read2_b32 v[50:51], v71 offset1:33
	v_mov_b32_e32 v55, v0
	v_mul_u32_u24_e32 v39, 0xb00, v39
	s_waitcnt lgkmcnt(0)
	v_cvt_pk_bf16_f32 v50, v50, v51
	ds_read2_b32 v[52:53], v71 offset0:66 offset1:99
	v_mov_b32_e32 v57, v0
	v_lshl_add_u64 v[54:55], v[8:9], 0, v[54:55]
	v_lshlrev_b32_e32 v56, 1, v39
	s_waitcnt lgkmcnt(0)
	v_cvt_pk_bf16_f32 v51, v52, v53
	ds_read2_b32 v[52:53], v71 offset0:132 offset1:165
	v_lshl_add_u64 v[56:57], v[54:55], 0, v[56:57]
	s_waitcnt lgkmcnt(0)
	v_cvt_pk_bf16_f32 v52, v52, v53
	ds_read2_b32 v[58:59], v71 offset0:198 offset1:231
	s_waitcnt lgkmcnt(0)
	v_cvt_pk_bf16_f32 v53, v58, v59
	flat_store_dwordx4 v[56:57], v[50:53]
	v_or_b32_e32 v39, v41, v72
	ds_read2_b32 v[50:51], v71 offset0:8 offset1:41
	v_mul_u32_u24_e32 v39, 0xb00, v39
	s_waitcnt lgkmcnt(0)
	v_cvt_pk_bf16_f32 v50, v50, v51
	ds_read2_b32 v[52:53], v71 offset0:74 offset1:107
	v_mov_b32_e32 v57, v0
	v_lshlrev_b32_e32 v56, 1, v39
	s_waitcnt lgkmcnt(0)
	v_cvt_pk_bf16_f32 v51, v52, v53
	ds_read2_b32 v[52:53], v71 offset0:140 offset1:173
	v_lshl_add_u64 v[56:57], v[54:55], 0, v[56:57]
	s_waitcnt lgkmcnt(0)
	v_cvt_pk_bf16_f32 v52, v52, v53
	ds_read2_b32 v[58:59], v71 offset0:206 offset1:239
	s_waitcnt lgkmcnt(0)
	v_cvt_pk_bf16_f32 v53, v58, v59
	flat_store_dwordx4 v[56:57], v[50:53]
	v_or_b32_e32 v39, v41, v73
	ds_read2_b32 v[50:51], v71 offset0:16 offset1:49
	v_mul_u32_u24_e32 v39, 0xb00, v39
	s_waitcnt lgkmcnt(0)
	v_cvt_pk_bf16_f32 v50, v50, v51
	ds_read2_b32 v[52:53], v71 offset0:82 offset1:115
	v_mov_b32_e32 v57, v0
	v_lshlrev_b32_e32 v56, 1, v39
	s_waitcnt lgkmcnt(0)
	v_cvt_pk_bf16_f32 v51, v52, v53
	ds_read2_b32 v[52:53], v71 offset0:148 offset1:181
	v_lshl_add_u64 v[56:57], v[54:55], 0, v[56:57]
	s_waitcnt lgkmcnt(0)
	v_cvt_pk_bf16_f32 v52, v52, v53
	ds_read2_b32 v[58:59], v71 offset0:214 offset1:247
	s_waitcnt lgkmcnt(0)
	v_cvt_pk_bf16_f32 v53, v58, v59
	flat_store_dwordx4 v[56:57], v[50:53]
	v_or_b32_e32 v39, v41, v74
	ds_read2_b32 v[50:51], v71 offset0:24 offset1:57
	v_mul_u32_u24_e32 v39, 0xb00, v39
	s_waitcnt lgkmcnt(0)
	v_cvt_pk_bf16_f32 v50, v50, v51
	ds_read2_b32 v[52:53], v71 offset0:90 offset1:123
	v_mov_b32_e32 v59, v0
	v_lshlrev_b32_e32 v58, 1, v39
	s_waitcnt lgkmcnt(0)
	v_cvt_pk_bf16_f32 v51, v52, v53
	ds_read2_b32 v[52:53], v71 offset0:156 offset1:189
	v_lshl_add_u64 v[54:55], v[54:55], 0, v[58:59]
	s_waitcnt lgkmcnt(0)
	v_cvt_pk_bf16_f32 v52, v52, v53
	ds_read2_b32 v[56:57], v71 offset0:222 offset1:255
	s_waitcnt lgkmcnt(0)
	v_cvt_pk_bf16_f32 v53, v56, v57
	flat_store_dwordx4 v[54:55], v[50:53]
	s_waitcnt lgkmcnt(0)

; template <int MAP>
; __device__ __forceinline__ void cvt_item(const float* W, int K, int N, bf16_t* Wt, int ldk, const float* gain, LAS float* scr, int item, int lane) {
;     ...
; #pragma unroll 8
;     for (int i = 0; i < 32; ++i) { const int kk = 2 * i + (lane >> 5); scr[kk * 33 + (lane & 31)] = W[(size_t)(k0 + kk) * N + n0 + (lane & 31)]; }
;     asm volatile("s_waitcnt lgkmcnt(0)" ::: "memory");
.LBB0_949:
	v_lshl_add_u64 v[66:67], v[64:65], 0, s[22:23]
	global_load_dword v192, v[66:67], off
	v_lshl_add_u64 v[66:67], v[62:63], 0, s[22:23]
	global_load_dword v193, v[66:67], off
	v_lshl_add_u64 v[66:67], v[60:61], 0, s[22:23]
	global_load_dword v194, v[66:67], off
	v_lshl_add_u64 v[66:67], v[58:59], 0, s[22:23]
	global_load_dword v195, v[66:67], off
	v_lshl_add_u64 v[66:67], v[56:57], 0, s[22:23]
	global_load_dword v196, v[66:67], off
	v_lshl_add_u64 v[66:67], v[54:55], 0, s[22:23]
	global_load_dword v197, v[66:67], off
	v_lshl_add_u64 v[66:67], v[52:53], 0, s[22:23]
	global_load_dword v198, v[66:67], off
	v_lshl_add_u64 v[66:67], v[50:51], 0, s[22:23]
	global_load_dword v199, v[66:67], off
	s_add_u32 s22, s22, 0x10000
	s_addc_u32 s23, s23, 0
	v_lshl_add_u64 v[66:67], v[64:65], 0, s[22:23]
	global_load_dword v200, v[66:67], off
	v_lshl_add_u64 v[66:67], v[62:63], 0, s[22:23]
	global_load_dword v201, v[66:67], off
	v_lshl_add_u64 v[66:67], v[60:61], 0, s[22:23]
	global_load_dword v202, v[66:67], off
	v_lshl_add_u64 v[66:67], v[58:59], 0, s[22:23]
	global_load_dword v203, v[66:67], off
	v_lshl_add_u64 v[66:67], v[56:57], 0, s[22:23]
	global_load_dword v204, v[66:67], off
	v_lshl_add_u64 v[66:67], v[54:55], 0, s[22:23]
	global_load_dword v205, v[66:67], off
	v_lshl_add_u64 v[66:67], v[52:53], 0, s[22:23]
	global_load_dword v206, v[66:67], off
	v_lshl_add_u64 v[66:67], v[50:51], 0, s[22:23]
	global_load_dword v207, v[66:67], off
	s_add_u32 s22, s22, 0x10000
	s_addc_u32 s23, s23, 0
	v_lshl_add_u64 v[66:67], v[64:65], 0, s[22:23]
	global_load_dword v208, v[66:67], off
	v_lshl_add_u64 v[66:67], v[62:63], 0, s[22:23]
	global_load_dword v209, v[66:67], off
	v_lshl_add_u64 v[66:67], v[60:61], 0, s[22:23]
	global_load_dword v210, v[66:67], off
	v_lshl_add_u64 v[66:67], v[58:59], 0, s[22:23]
	global_load_dword v211, v[66:67], off
	v_lshl_add_u64 v[66:67], v[56:57], 0, s[22:23]
	global_load_dword v212, v[66:67], off
	v_lshl_add_u64 v[66:67], v[54:55], 0, s[22:23]
	global_load_dword v213, v[66:67], off
	v_lshl_add_u64 v[66:67], v[52:53], 0, s[22:23]
	global_load_dword v214, v[66:67], off
	v_lshl_add_u64 v[66:67], v[50:51], 0, s[22:23]
	global_load_dword v215, v[66:67], off
	s_add_u32 s22, s22, 0x10000
	s_addc_u32 s23, s23, 0
	v_lshl_add_u64 v[66:67], v[64:65], 0, s[22:23]
	global_load_dword v216, v[66:67], off
	v_lshl_add_u64 v[66:67], v[62:63], 0, s[22:23]
	global_load_dword v217, v[66:67], off
	v_lshl_add_u64 v[66:67], v[60:61], 0, s[22:23]
	global_load_dword v218, v[66:67], off
	v_lshl_add_u64 v[66:67], v[58:59], 0, s[22:23]
	global_load_dword v219, v[66:67], off
	v_lshl_add_u64 v[66:67], v[56:57], 0, s[22:23]
	global_load_dword v220, v[66:67], off
	v_lshl_add_u64 v[66:67], v[54:55], 0, s[22:23]
	global_load_dword v221, v[66:67], off
	v_lshl_add_u64 v[66:67], v[52:53], 0, s[22:23]
	global_load_dword v222, v[66:67], off
	v_lshl_add_u64 v[66:67], v[50:51], 0, s[22:23]
	global_load_dword v223, v[66:67], off
	s_add_u32 s22, s22, 0x10000
	s_addc_u32 s23, s23, 0
	s_waitcnt vmcnt(24)
	ds_write_b32 v39, v192
	ds_write_b32 v39, v193 offset:264
	ds_write_b32 v39, v194 offset:528
	ds_write_b32 v39, v195 offset:792
	ds_write_b32 v39, v196 offset:1056
	ds_write_b32 v39, v197 offset:1320
	ds_write_b32 v39, v198 offset:1584
	ds_write_b32 v39, v199 offset:1848
	v_add_u32_e32 v39, 0x840, v39
	s_waitcnt vmcnt(16)
	ds_write_b32 v39, v200
	ds_write_b32 v39, v201 offset:264
	ds_write_b32 v39, v202 offset:528
	ds_write_b32 v39, v203 offset:792
	ds_write_b32 v39, v204 offset:1056
	ds_write_b32 v39, v205 offset:1320
	ds_write_b32 v39, v206 offset:1584
	ds_write_b32 v39, v207 offset:1848
	v_add_u32_e32 v39, 0x840, v39
	s_waitcnt vmcnt(8)
; #define LAS __attribute__((address_space(3)))
; __device__ __forceinline__ unsigned cvt_pk_bf16(float lo, float hi) { unsigned r; asm volatile("v_cvt_pk_bf16_f32 %0, %1, %2" : "=v"(r) : "v"(lo), "v"(hi)); return r; }
; template <int MAP>
; __device__ __forceinline__ void cvt_item(const float* W, int K, int N, bf16_t* Wt, int ldk, const float* gain, LAS float* scr, int item, int lane) {
;     ...
;     for (int i = 0; i < 32; ++i) { const int kk = 2 * i + (lane >> 5); scr[kk * 33 + (lane & 31)] = W[(size_t)(k0 + kk) * N + n0 + (lane & 31)]; }
;     asm volatile("s_waitcnt lgkmcnt(0)" ::: "memory");
;     const int c = lane & 7;
;     float gk[8];
; #pragma unroll
;     for (int j = 0; j < 8; ++j) gk[j] = gain ? gain[k0 + 8 * c + j] : 1.0f;
; #pragma unroll
;     for (int j = 0; j < 4; ++j) { const int n = (lane >> 3) + 8 * j; const LAS float* s = scr + (8 * c) * 33 + n;
;         u32x4 o; o.x = cvt_pk_bf16(s[0 * 33] * gk[0], s[1 * 33] * gk[1]); o.y = cvt_pk_bf16(s[2 * 33] * gk[2], s[3 * 33] * gk[3]);
;         o.z = cvt_pk_bf16(s[4 * 33] * gk[4], s[5 * 33] * gk[5]); o.w = cvt_pk_bf16(s[6 * 33] * gk[6], s[7 * 33] * gk[7]);
;         const int ng = n0 + n; int drow = ng;
;         if (MAP == 1) { const int half = ng / DFF, r = ng % DFF; drow = (r / 128) * 256 + half * 128 + (r % 128); }
;         if (MAP == 2) { drow = ng < 1536 ? ng + 1024 : (ng < 2560 ? ng - 1536 : ng); }
;         *(u32x4*)(Wt + (size_t)drow * ldk + k0 + 8 * c) = o; }
;     asm volatile("s_waitcnt lgkmcnt(0)" ::: "memory");
	ds_write_b32 v39, v208
	ds_write_b32 v39, v209 offset:264
	ds_write_b32 v39, v210 offset:528
	ds_write_b32 v39, v211 offset:792
	ds_write_b32 v39, v212 offset:1056
	ds_write_b32 v39, v213 offset:1320
	ds_write_b32 v39, v214 offset:1584
	ds_write_b32 v39, v215 offset:1848
	v_add_u32_e32 v39, 0x840, v39
	s_waitcnt vmcnt(0)
	ds_write_b32 v39, v216
	ds_write_b32 v39, v217 offset:264
	ds_write_b32 v39, v218 offset:528
	ds_write_b32 v39, v219 offset:792
	ds_write_b32 v39, v220 offset:1056
	ds_write_b32 v39, v221 offset:1320
	ds_write_b32 v39, v222 offset:1584
	ds_write_b32 v39, v223 offset:1848
	v_add_u32_e32 v39, 0x840, v39
	v_lshl_add_u32 v39, v1, 1, v189
	v_lshlrev_b32_e32 v41, 5, v1
	v_and_b32_e32 v39, 0x1ffc0, v39
	v_and_b32_e32 v41, 0x3e0, v41
	s_waitcnt lgkmcnt(0)
	v_lshlrev_b32_e32 v54, 1, v39
	v_or_b32_e32 v39, v41, v70
	ds_read2_b32 v[50:51], v71 offset1:33
	v_mov_b32_e32 v55, v0
	v_mul_u32_u24_e32 v39, 0xb00, v39
	s_waitcnt lgkmcnt(0)
	v_cvt_pk_bf16_f32 v50, v50, v51
	ds_read2_b32 v[52:53], v71 offset0:66 offset1:99
	v_mov_b32_e32 v57, v0
	v_lshl_add_u64 v[54:55], v[10:11], 0, v[54:55]
	v_lshlrev_b32_e32 v56, 1, v39
	s_waitcnt lgkmcnt(0)
	v_cvt_pk_bf16_f32 v51, v52, v53
	ds_read2_b32 v[52:53], v71 offset0:132 offset1:165
	v_lshl_add_u64 v[56:57], v[54:55], 0, v[56:57]
	s_waitcnt lgkmcnt(0)
	v_cvt_pk_bf16_f32 v52, v52, v53
	ds_read2_b32 v[58:59], v71 offset0:198 offset1:231
	s_waitcnt lgkmcnt(0)
	v_cvt_pk_bf16_f32 v53, v58, v59
	flat_store_dwordx4 v[56:57], v[50:53]
	v_or_b32_e32 v39, v41, v72
	ds_read2_b32 v[50:51], v71 offset0:8 offset1:41
	v_mul_u32_u24_e32 v39, 0xb00, v39
	s_waitcnt lgkmcnt(0)
	v_cvt_pk_bf16_f32 v50, v50, v51
	ds_read2_b32 v[52:53], v71 offset0:74 offset1:107
	v_mov_b32_e32 v57, v0
	v_lshlrev_b32_e32 v56, 1, v39
	s_waitcnt lgkmcnt(0)
	v_cvt_pk_bf16_f32 v51, v52, v53
	ds_read2_b32 v[52:53], v71 offset0:140 offset1:173
	v_lshl_add_u64 v[56:57], v[54:55], 0, v[56:57]
	s_waitcnt lgkmcnt(0)
	v_cvt_pk_bf16_f32 v52, v52, v53
	ds_read2_b32 v[58:59], v71 offset0:206 offset1:239
	s_waitcnt lgkmcnt(0)
	v_cvt_pk_bf16_f32 v53, v58, v59
	flat_store_dwordx4 v[56:57], v[50:53]
	v_or_b32_e32 v39, v41, v73
	ds_read2_b32 v[50:51], v71 offset0:16 offset1:49
	v_mul_u32_u24_e32 v39, 0xb00, v39
	s_waitcnt lgkmcnt(0)
	v_cvt_pk_bf16_f32 v50, v50, v51
	ds_read2_b32 v[52:53], v71 offset0:82 offset1:115
	v_mov_b32_e32 v57, v0
	v_lshlrev_b32_e32 v56, 1, v39
	s_waitcnt lgkmcnt(0)
	v_cvt_pk_bf16_f32 v51, v52, v53
	ds_read2_b32 v[52:53], v71 offset0:148 offset1:181
	v_lshl_add_u64 v[56:57], v[54:55], 0, v[56:57]
	s_waitcnt lgkmcnt(0)
	v_cvt_pk_bf16_f32 v52, v52, v53
	ds_read2_b32 v[58:59], v71 offset0:214 offset1:247
	s_waitcnt lgkmcnt(0)
	v_cvt_pk_bf16_f32 v53, v58, v59
	flat_store_dwordx4 v[56:57], v[50:53]
	v_or_b32_e32 v39, v41, v74
	ds_read2_b32 v[50:51], v71 offset0:24 offset1:57
	v_mul_u32_u24_e32 v39, 0xb00, v39
	s_waitcnt lgkmcnt(0)
	v_cvt_pk_bf16_f32 v50, v50, v51
	ds_read2_b32 v[52:53], v71 offset0:90 offset1:123
	v_mov_b32_e32 v59, v0
	v_lshlrev_b32_e32 v58, 1, v39
	s_waitcnt lgkmcnt(0)
	v_cvt_pk_bf16_f32 v51, v52, v53
	ds_read2_b32 v[52:53], v71 offset0:156 offset1:189
	v_lshl_add_u64 v[54:55], v[54:55], 0, v[58:59]
	s_waitcnt lgkmcnt(0)
	v_cvt_pk_bf16_f32 v52, v52, v53
	ds_read2_b32 v[56:57], v71 offset0:222 offset1:255
	s_waitcnt lgkmcnt(0)
	v_cvt_pk_bf16_f32 v53, v56, v57
	flat_store_dwordx4 v[54:55], v[50:53]
	s_waitcnt lgkmcnt(0)

; template <int MAP>
; __device__ __forceinline__ void cvt_item(const float* W, int K, int N, bf16_t* Wt, int ldk, const float* gain, LAS float* scr, int item, int lane) {
;     ...
; #pragma unroll 8
;     for (int i = 0; i < 32; ++i) { const int kk = 2 * i + (lane >> 5); scr[kk * 33 + (lane & 31)] = W[(size_t)(k0 + kk) * N + n0 + (lane & 31)]; }
;     asm volatile("s_waitcnt lgkmcnt(0)" ::: "memory");
;     const int c = lane & 7;
;     float gk[8];
; #pragma unroll
;     for (int j = 0; j < 8; ++j) gk[j] = gain ? gain[k0 + 8 * c + j] : 1.0f;
.LBB0_954:
	v_lshl_add_u64 v[66:67], v[64:65], 0, s[2:3]
	global_load_dword v192, v[66:67], off
	v_lshl_add_u64 v[66:67], v[62:63], 0, s[2:3]
	global_load_dword v193, v[66:67], off
	v_lshl_add_u64 v[66:67], v[60:61], 0, s[2:3]
	global_load_dword v194, v[66:67], off
	v_lshl_add_u64 v[66:67], v[58:59], 0, s[2:3]
	global_load_dword v195, v[66:67], off
	v_lshl_add_u64 v[66:67], v[56:57], 0, s[2:3]
	global_load_dword v196, v[66:67], off
	v_lshl_add_u64 v[66:67], v[54:55], 0, s[2:3]
	global_load_dword v197, v[66:67], off
	v_lshl_add_u64 v[66:67], v[52:53], 0, s[2:3]
	global_load_dword v198, v[66:67], off
	v_lshl_add_u64 v[66:67], v[50:51], 0, s[2:3]
	global_load_dword v199, v[66:67], off
	s_add_u32 s2, s2, 0x58000
	s_addc_u32 s3, s3, 0
	v_lshl_add_u64 v[66:67], v[64:65], 0, s[2:3]
	global_load_dword v200, v[66:67], off
	v_lshl_add_u64 v[66:67], v[62:63], 0, s[2:3]
	global_load_dword v201, v[66:67], off
	v_lshl_add_u64 v[66:67], v[60:61], 0, s[2:3]
	global_load_dword v202, v[66:67], off
	v_lshl_add_u64 v[66:67], v[58:59], 0, s[2:3]
	global_load_dword v203, v[66:67], off
	v_lshl_add_u64 v[66:67], v[56:57], 0, s[2:3]
	global_load_dword v204, v[66:67], off
	v_lshl_add_u64 v[66:67], v[54:55], 0, s[2:3]
	global_load_dword v205, v[66:67], off
	v_lshl_add_u64 v[66:67], v[52:53], 0, s[2:3]
	global_load_dword v206, v[66:67], off
	v_lshl_add_u64 v[66:67], v[50:51], 0, s[2:3]
	global_load_dword v207, v[66:67], off
	s_add_u32 s2, s2, 0x58000
	s_addc_u32 s3, s3, 0
	v_lshl_add_u64 v[66:67], v[64:65], 0, s[2:3]
	global_load_dword v208, v[66:67], off
	v_lshl_add_u64 v[66:67], v[62:63], 0, s[2:3]
	global_load_dword v209, v[66:67], off
	v_lshl_add_u64 v[66:67], v[60:61], 0, s[2:3]
	global_load_dword v210, v[66:67], off
	v_lshl_add_u64 v[66:67], v[58:59], 0, s[2:3]
	global_load_dword v211, v[66:67], off
	v_lshl_add_u64 v[66:67], v[56:57], 0, s[2:3]
	global_load_dword v212, v[66:67], off
	v_lshl_add_u64 v[66:67], v[54:55], 0, s[2:3]
	global_load_dword v213, v[66:67], off
	v_lshl_add_u64 v[66:67], v[52:53], 0, s[2:3]
	global_load_dword v214, v[66:67], off
	v_lshl_add_u64 v[66:67], v[50:51], 0, s[2:3]
	global_load_dword v215, v[66:67], off
	s_add_u32 s2, s2, 0x58000
	s_addc_u32 s3, s3, 0
	v_lshl_add_u64 v[66:67], v[64:65], 0, s[2:3]
	global_load_dword v216, v[66:67], off
	v_lshl_add_u64 v[66:67], v[62:63], 0, s[2:3]
	global_load_dword v217, v[66:67], off
	v_lshl_add_u64 v[66:67], v[60:61], 0, s[2:3]
	global_load_dword v218, v[66:67], off
	v_lshl_add_u64 v[66:67], v[58:59], 0, s[2:3]
	global_load_dword v219, v[66:67], off
	v_lshl_add_u64 v[66:67], v[56:57], 0, s[2:3]
	global_load_dword v220, v[66:67], off
	v_lshl_add_u64 v[66:67], v[54:55], 0, s[2:3]
	global_load_dword v221, v[66:67], off
	v_lshl_add_u64 v[66:67], v[52:53], 0, s[2:3]
	global_load_dword v222, v[66:67], off
	v_lshl_add_u64 v[66:67], v[50:51], 0, s[2:3]
	global_load_dword v223, v[66:67], off
	s_add_u32 s2, s2, 0x58000
	s_addc_u32 s3, s3, 0
	s_waitcnt vmcnt(24)
	ds_write_b32 v45, v192
	ds_write_b32 v45, v193 offset:264
	ds_write_b32 v45, v194 offset:528
	ds_write_b32 v45, v195 offset:792
	ds_write_b32 v45, v196 offset:1056
	ds_write_b32 v45, v197 offset:1320
	ds_write_b32 v45, v198 offset:1584
	ds_write_b32 v45, v199 offset:1848
	v_add_u32_e32 v45, 0x840, v45
	s_waitcnt vmcnt(16)
	ds_write_b32 v45, v200
	ds_write_b32 v45, v201 offset:264
	ds_write_b32 v45, v202 offset:528
	ds_write_b32 v45, v203 offset:792
	ds_write_b32 v45, v204 offset:1056
	ds_write_b32 v45, v205 offset:1320
	ds_write_b32 v45, v206 offset:1584
	ds_write_b32 v45, v207 offset:1848
	v_add_u32_e32 v45, 0x840, v45
	s_waitcnt vmcnt(8)
	ds_write_b32 v45, v208
	ds_write_b32 v45, v209 offset:264
	ds_write_b32 v45, v210 offset:528
	ds_write_b32 v45, v211 offset:792
	ds_write_b32 v45, v212 offset:1056
	ds_write_b32 v45, v213 offset:1320
	ds_write_b32 v45, v214 offset:1584
	ds_write_b32 v45, v215 offset:1848
	v_add_u32_e32 v45, 0x840, v45
	s_waitcnt vmcnt(0)
	ds_write_b32 v45, v216
	ds_write_b32 v45, v217 offset:264
	ds_write_b32 v45, v218 offset:528
	ds_write_b32 v45, v219 offset:792
	ds_write_b32 v45, v220 offset:1056
	ds_write_b32 v45, v221 offset:1320
	ds_write_b32 v45, v222 offset:1584
	ds_write_b32 v45, v223 offset:1848
	v_add_u32_e32 v45, 0x840, v45
	s_lshl_b64 s[2:3], s[10:11], 2
	s_add_u32 s22, s24, s2
	s_addc_u32 s23, s25, s3
	v_lshlrev_b16_e32 v56, 6, v43
	s_waitcnt lgkmcnt(0)
	s_cmp_lg_u64 s[24:25], 0
	s_cselect_b64 s[24:25], -1, 0
	v_or_b32_e32 v45, v75, v56
	v_mov_b32_e32 v43, 1.0
	s_and_b64 vcc, exec, s[24:25]
	v_lshlrev_b32_e32 v50, 2, v45
	v_mov_b32_e32 v45, 1.0
	s_cbranch_vccz .LBB0_957
	v_mov_b32_e32 v51, v0
	v_lshl_add_u64 v[52:53], s[22:23], 0, v[50:51]
	flat_load_dword v45, v[52:53]

; template <int MAP>
; __device__ __forceinline__ void cvt_item(const float* W, int K, int N, bf16_t* Wt, int ldk, const float* gain, LAS float* scr, int item, int lane) {
;     ...
; #pragma unroll 8
;     for (int i = 0; i < 32; ++i) { const int kk = 2 * i + (lane >> 5); scr[kk * 33 + (lane & 31)] = W[(size_t)(k0 + kk) * N + n0 + (lane & 31)]; }
;     asm volatile("s_waitcnt lgkmcnt(0)" ::: "memory");
;     const int c = lane & 7;
;     float gk[8];
; #pragma unroll
;     for (int j = 0; j < 8; ++j) gk[j] = gain ? gain[k0 + 8 * c + j] : 1.0f;
.LBB0_975:
	v_lshl_add_u64 v[66:67], v[64:65], 0, s[2:3]
	global_load_dword v192, v[66:67], off
	v_lshl_add_u64 v[66:67], v[62:63], 0, s[2:3]
	global_load_dword v193, v[66:67], off
	v_lshl_add_u64 v[66:67], v[60:61], 0, s[2:3]
	global_load_dword v194, v[66:67], off
	v_lshl_add_u64 v[66:67], v[58:59], 0, s[2:3]
	global_load_dword v195, v[66:67], off
	v_lshl_add_u64 v[66:67], v[56:57], 0, s[2:3]
	global_load_dword v196, v[66:67], off
	v_lshl_add_u64 v[66:67], v[54:55], 0, s[2:3]
	global_load_dword v197, v[66:67], off
	v_lshl_add_u64 v[66:67], v[52:53], 0, s[2:3]
	global_load_dword v198, v[66:67], off
	v_lshl_add_u64 v[66:67], v[50:51], 0, s[2:3]
	global_load_dword v199, v[66:67], off
	s_add_u32 s2, s2, 0x58000
	s_addc_u32 s3, s3, 0
	v_lshl_add_u64 v[66:67], v[64:65], 0, s[2:3]
	global_load_dword v200, v[66:67], off
	v_lshl_add_u64 v[66:67], v[62:63], 0, s[2:3]
	global_load_dword v201, v[66:67], off
	v_lshl_add_u64 v[66:67], v[60:61], 0, s[2:3]
	global_load_dword v202, v[66:67], off
	v_lshl_add_u64 v[66:67], v[58:59], 0, s[2:3]
	global_load_dword v203, v[66:67], off
	v_lshl_add_u64 v[66:67], v[56:57], 0, s[2:3]
	global_load_dword v204, v[66:67], off
	v_lshl_add_u64 v[66:67], v[54:55], 0, s[2:3]
	global_load_dword v205, v[66:67], off
	v_lshl_add_u64 v[66:67], v[52:53], 0, s[2:3]
	global_load_dword v206, v[66:67], off
	v_lshl_add_u64 v[66:67], v[50:51], 0, s[2:3]
	global_load_dword v207, v[66:67], off
	s_add_u32 s2, s2, 0x58000
	s_addc_u32 s3, s3, 0
	v_lshl_add_u64 v[66:67], v[64:65], 0, s[2:3]
	global_load_dword v208, v[66:67], off
	v_lshl_add_u64 v[66:67], v[62:63], 0, s[2:3]
	global_load_dword v209, v[66:67], off
	v_lshl_add_u64 v[66:67], v[60:61], 0, s[2:3]
	global_load_dword v210, v[66:67], off
	v_lshl_add_u64 v[66:67], v[58:59], 0, s[2:3]
	global_load_dword v211, v[66:67], off
	v_lshl_add_u64 v[66:67], v[56:57], 0, s[2:3]
	global_load_dword v212, v[66:67], off
	v_lshl_add_u64 v[66:67], v[54:55], 0, s[2:3]
	global_load_dword v213, v[66:67], off
	v_lshl_add_u64 v[66:67], v[52:53], 0, s[2:3]
	global_load_dword v214, v[66:67], off
	v_lshl_add_u64 v[66:67], v[50:51], 0, s[2:3]
	global_load_dword v215, v[66:67], off
	s_add_u32 s2, s2, 0x58000
	s_addc_u32 s3, s3, 0
	v_lshl_add_u64 v[66:67], v[64:65], 0, s[2:3]
	global_load_dword v216, v[66:67], off
	v_lshl_add_u64 v[66:67], v[62:63], 0, s[2:3]
	global_load_dword v217, v[66:67], off
	v_lshl_add_u64 v[66:67], v[60:61], 0, s[2:3]
	global_load_dword v218, v[66:67], off
	v_lshl_add_u64 v[66:67], v[58:59], 0, s[2:3]
	global_load_dword v219, v[66:67], off
	v_lshl_add_u64 v[66:67], v[56:57], 0, s[2:3]
	global_load_dword v220, v[66:67], off
	v_lshl_add_u64 v[66:67], v[54:55], 0, s[2:3]
	global_load_dword v221, v[66:67], off
	v_lshl_add_u64 v[66:67], v[52:53], 0, s[2:3]
	global_load_dword v222, v[66:67], off
	v_lshl_add_u64 v[66:67], v[50:51], 0, s[2:3]
	global_load_dword v223, v[66:67], off
	s_add_u32 s2, s2, 0x58000
	s_addc_u32 s3, s3, 0
	s_waitcnt vmcnt(24)
	ds_write_b32 v43, v192
	ds_write_b32 v43, v193 offset:264
	ds_write_b32 v43, v194 offset:528
	ds_write_b32 v43, v195 offset:792
	ds_write_b32 v43, v196 offset:1056
	ds_write_b32 v43, v197 offset:1320
	ds_write_b32 v43, v198 offset:1584
	ds_write_b32 v43, v199 offset:1848
	v_add_u32_e32 v43, 0x840, v43
	s_waitcnt vmcnt(16)
	ds_write_b32 v43, v200
	ds_write_b32 v43, v201 offset:264
	ds_write_b32 v43, v202 offset:528
	ds_write_b32 v43, v203 offset:792
	ds_write_b32 v43, v204 offset:1056
	ds_write_b32 v43, v205 offset:1320
	ds_write_b32 v43, v206 offset:1584
	ds_write_b32 v43, v207 offset:1848
	v_add_u32_e32 v43, 0x840, v43
	s_waitcnt vmcnt(8)
	ds_write_b32 v43, v208
	ds_write_b32 v43, v209 offset:264
	ds_write_b32 v43, v210 offset:528
	ds_write_b32 v43, v211 offset:792
	ds_write_b32 v43, v212 offset:1056
	ds_write_b32 v43, v213 offset:1320
	ds_write_b32 v43, v214 offset:1584
	ds_write_b32 v43, v215 offset:1848
	v_add_u32_e32 v43, 0x840, v43
	s_waitcnt vmcnt(0)
	ds_write_b32 v43, v216
	ds_write_b32 v43, v217 offset:264
	ds_write_b32 v43, v218 offset:528
	ds_write_b32 v43, v219 offset:792
	ds_write_b32 v43, v220 offset:1056
	ds_write_b32 v43, v221 offset:1320
	ds_write_b32 v43, v222 offset:1584
	ds_write_b32 v43, v223 offset:1848
	v_add_u32_e32 v43, 0x840, v43
	s_lshl_b64 s[2:3], s[10:11], 2
	s_add_u32 s20, s22, s2
	s_addc_u32 s21, s23, s3
	s_waitcnt lgkmcnt(0)
	s_cmp_lg_u64 s[22:23], 0
	s_cselect_b64 s[22:23], -1, 0
	v_or_b32_e32 v45, v75, v47
	v_mov_b32_e32 v43, 1.0
	s_and_b64 vcc, exec, s[22:23]
	v_lshlrev_b32_e32 v50, 2, v45
	v_mov_b32_e32 v45, 1.0
	s_cbranch_vccz .LBB0_978
	v_mov_b32_e32 v51, v0
	v_lshl_add_u64 v[52:53], s[20:21], 0, v[50:51]
	flat_load_dword v45, v[52:53]

; template <int MAP>
; __device__ __forceinline__ void cvt_item(const float* W, int K, int N, bf16_t* Wt, int ldk, const float* gain, LAS float* scr, int item, int lane) {
;     ...
; #pragma unroll 8
;     for (int i = 0; i < 32; ++i) { const int kk = 2 * i + (lane >> 5); scr[kk * 33 + (lane & 31)] = W[(size_t)(k0 + kk) * N + n0 + (lane & 31)]; }
;     asm volatile("s_waitcnt lgkmcnt(0)" ::: "memory");
;     const int c = lane & 7;
;     float gk[8];
; #pragma unroll
;     for (int j = 0; j < 8; ++j) gk[j] = gain ? gain[k0 + 8 * c + j] : 1.0f;
.LBB0_996:
	v_lshl_add_u64 v[106:107], v[68:69], 0, s[2:3]
	global_load_dword v192, v[106:107], off
	v_lshl_add_u64 v[106:107], v[66:67], 0, s[2:3]
	global_load_dword v193, v[106:107], off
	v_lshl_add_u64 v[106:107], v[64:65], 0, s[2:3]
	global_load_dword v194, v[106:107], off
	v_lshl_add_u64 v[106:107], v[62:63], 0, s[2:3]
	global_load_dword v195, v[106:107], off
	v_lshl_add_u64 v[106:107], v[60:61], 0, s[2:3]
	global_load_dword v196, v[106:107], off
	v_lshl_add_u64 v[106:107], v[58:59], 0, s[2:3]
	global_load_dword v197, v[106:107], off
	v_lshl_add_u64 v[106:107], v[56:57], 0, s[2:3]
	global_load_dword v198, v[106:107], off
	v_lshl_add_u64 v[106:107], v[54:55], 0, s[2:3]
	global_load_dword v199, v[106:107], off
	s_add_u32 s2, s2, 0x58000
	s_addc_u32 s3, s3, 0
	v_lshl_add_u64 v[106:107], v[68:69], 0, s[2:3]
	global_load_dword v200, v[106:107], off
	v_lshl_add_u64 v[106:107], v[66:67], 0, s[2:3]
	global_load_dword v201, v[106:107], off
	v_lshl_add_u64 v[106:107], v[64:65], 0, s[2:3]
	global_load_dword v202, v[106:107], off
	v_lshl_add_u64 v[106:107], v[62:63], 0, s[2:3]
	global_load_dword v203, v[106:107], off
	v_lshl_add_u64 v[106:107], v[60:61], 0, s[2:3]
	global_load_dword v204, v[106:107], off
	v_lshl_add_u64 v[106:107], v[58:59], 0, s[2:3]
	global_load_dword v205, v[106:107], off
	v_lshl_add_u64 v[106:107], v[56:57], 0, s[2:3]
	global_load_dword v206, v[106:107], off
	v_lshl_add_u64 v[106:107], v[54:55], 0, s[2:3]
	global_load_dword v207, v[106:107], off
	s_add_u32 s2, s2, 0x58000
	s_addc_u32 s3, s3, 0
	v_lshl_add_u64 v[106:107], v[68:69], 0, s[2:3]
	global_load_dword v208, v[106:107], off
	v_lshl_add_u64 v[106:107], v[66:67], 0, s[2:3]
	global_load_dword v209, v[106:107], off
	v_lshl_add_u64 v[106:107], v[64:65], 0, s[2:3]
	global_load_dword v210, v[106:107], off
	v_lshl_add_u64 v[106:107], v[62:63], 0, s[2:3]
	global_load_dword v211, v[106:107], off
	v_lshl_add_u64 v[106:107], v[60:61], 0, s[2:3]
	global_load_dword v212, v[106:107], off
	v_lshl_add_u64 v[106:107], v[58:59], 0, s[2:3]
	global_load_dword v213, v[106:107], off
	v_lshl_add_u64 v[106:107], v[56:57], 0, s[2:3]
	global_load_dword v214, v[106:107], off
	v_lshl_add_u64 v[106:107], v[54:55], 0, s[2:3]
	global_load_dword v215, v[106:107], off
	s_add_u32 s2, s2, 0x58000
	s_addc_u32 s3, s3, 0
	v_lshl_add_u64 v[106:107], v[68:69], 0, s[2:3]
	global_load_dword v216, v[106:107], off
	v_lshl_add_u64 v[106:107], v[66:67], 0, s[2:3]
	global_load_dword v217, v[106:107], off
	v_lshl_add_u64 v[106:107], v[64:65], 0, s[2:3]
	global_load_dword v218, v[106:107], off
	v_lshl_add_u64 v[106:107], v[62:63], 0, s[2:3]
	global_load_dword v219, v[106:107], off
	v_lshl_add_u64 v[106:107], v[60:61], 0, s[2:3]
	global_load_dword v220, v[106:107], off
	v_lshl_add_u64 v[106:107], v[58:59], 0, s[2:3]
	global_load_dword v221, v[106:107], off
	v_lshl_add_u64 v[106:107], v[56:57], 0, s[2:3]
	global_load_dword v222, v[106:107], off
	v_lshl_add_u64 v[106:107], v[54:55], 0, s[2:3]
	global_load_dword v223, v[106:107], off
	s_add_u32 s2, s2, 0x58000
	s_addc_u32 s3, s3, 0
	s_waitcnt vmcnt(24)
	ds_write_b32 v39, v192
	ds_write_b32 v39, v193 offset:264
	ds_write_b32 v39, v194 offset:528
	ds_write_b32 v39, v195 offset:792
	ds_write_b32 v39, v196 offset:1056
	ds_write_b32 v39, v197 offset:1320
	ds_write_b32 v39, v198 offset:1584
	ds_write_b32 v39, v199 offset:1848
	v_add_u32_e32 v39, 0x840, v39
	s_waitcnt vmcnt(16)
	ds_write_b32 v39, v200
	ds_write_b32 v39, v201 offset:264
	ds_write_b32 v39, v202 offset:528
	ds_write_b32 v39, v203 offset:792
	ds_write_b32 v39, v204 offset:1056
	ds_write_b32 v39, v205 offset:1320
	ds_write_b32 v39, v206 offset:1584
	ds_write_b32 v39, v207 offset:1848
	v_add_u32_e32 v39, 0x840, v39
	s_waitcnt vmcnt(8)
	ds_write_b32 v39, v208
	ds_write_b32 v39, v209 offset:264
	ds_write_b32 v39, v210 offset:528
	ds_write_b32 v39, v211 offset:792
	ds_write_b32 v39, v212 offset:1056
	ds_write_b32 v39, v213 offset:1320
	ds_write_b32 v39, v214 offset:1584
	ds_write_b32 v39, v215 offset:1848
	v_add_u32_e32 v39, 0x840, v39
	s_waitcnt vmcnt(0)
	ds_write_b32 v39, v216
	ds_write_b32 v39, v217 offset:264
	ds_write_b32 v39, v218 offset:528
	ds_write_b32 v39, v219 offset:792
	ds_write_b32 v39, v220 offset:1056
	ds_write_b32 v39, v221 offset:1320
	ds_write_b32 v39, v222 offset:1584
	ds_write_b32 v39, v223 offset:1848
	v_add_u32_e32 v39, 0x840, v39
	s_lshl_b64 s[2:3], s[10:11], 2
	s_add_u32 s18, s20, s2
	s_addc_u32 s19, s21, s3
	s_waitcnt lgkmcnt(0)
	s_cmp_lg_u64 s[20:21], 0
	s_cselect_b64 s[20:21], -1, 0
	v_or_b32_e32 v54, v52, v75
	v_mov_b32_e32 v39, 1.0
	s_and_b64 vcc, exec, s[20:21]
	v_ashrrev_i32_e32 v55, 31, v54
	v_mov_b32_e32 v41, 1.0
	s_cbranch_vccz .LBB0_999
	v_lshl_add_u64 v[56:57], v[54:55], 2, s[18:19]
	flat_load_dword v41, v[56:57]
